# DA unit epilogue: packed f32 (v_pk_mul/add/fma) for the accumulator scaling, the partner-half add, the sum of squares, the silu division steps and the final gain products (same IEEE division sequence)
# speedup vs baseline: 1.1118x; 1.0003x over previous
; __device__ void da_unit(char* lds, const Params& p, int layer, int unit) {
;     ...
;             for (int g = 0; g < 4; ++g) gwv[k * 4 + g] = *(const u32x2*)(p.z + ZS_GATE + tokq * 1024 + h * 128 + 32 * k + 8 * g + 4 * h2);
;     }
;     const float lsum = lrow + __shfl_xor(lrow, 32);
;     float* xch = (float*)lds + qg * 4096;
;     if (c == 1) {
;         const float i1 = lam / lsum;
; #pragma unroll
;         for (int k = 0; k < 4; ++k)
; #pragma unroll
;             for (int e = 0; e < 16; ++e) xch[(k * 16 + e) * 64 + lane] = O[k][e] * i1;
;     }
;     __syncthreads();
;     if (c == 0) {
;         const float i0 = 1.0f / lsum;
;         float ss = 0.f;
; #pragma unroll
;         for (int k = 0; k < 4; ++k)
; #pragma unroll
;             for (int e = 0; e < 16; ++e) { const float a = O[k][e] * i0 - xch[(k * 16 + e) * 64 + lane]; O[k][e] = a; ss += a * a; }
.LBB0_525:
	s_or_b64 exec, exec, s[4:5]
	s_ashr_i32 s0, s6, 2
	s_ashr_i32 s1, s0, 31
	s_ashr_i32 s2, s7, 31
	s_lshl_b64 s[0:1], s[0:1], 11
	s_add_u32 s0, s0, s7
	s_addc_u32 s1, s1, s2
	s_cmp_eq_u32 s15, 0
	v_or_b32_e32 v64, s0, v147
	v_mov_b32_e32 v65, s1
	s_cselect_b64 s[0:1], -1, 0
	s_cmp_lg_u32 s15, 0
	s_cselect_b64 s[2:3], -1, 0
	s_and_b64 vcc, exec, s[2:3]
	v_lshlrev_b64 v[78:79], 11, v[64:65]
	v_mov_b32_e32 v253, v153
	s_lshl_b32 s70, s12, 8
	s_lshl_b32 s0, s15, 7
	s_add_i32 s70, s70, s0
	v_readlane_b32 s4, v254, 20
	v_readlane_b32 s5, v254, 21
	s_load_dword s2, s[86:87], 0xa0
	ds_bpermute_b32 v65, v244, v193
	s_nop 0
	v_lshl_add_u64 v[76:77], s[4:5], 0, v[78:79]
	v_lshl_add_u64 v[76:77], v[76:77], 0, s[70:71]
	v_lshl_add_u64 v[76:77], v[76:77], 0, v[252:253]
	global_load_dwordx2 v[200:201], v[76:77], off offset:0
	global_load_dwordx2 v[202:203], v[76:77], off offset:16
	global_load_dwordx2 v[204:205], v[76:77], off offset:32
	global_load_dwordx2 v[206:207], v[76:77], off offset:48
	global_load_dwordx2 v[208:209], v[76:77], off offset:64
	global_load_dwordx2 v[210:211], v[76:77], off offset:80
	global_load_dwordx2 v[212:213], v[76:77], off offset:96
	global_load_dwordx2 v[214:215], v[76:77], off offset:112
	v_lshl_add_u64 v[78:79], s[62:63], 0, v[78:79]
	v_lshl_add_u64 v[78:79], v[78:79], 0, s[70:71]
	v_lshl_add_u64 v[78:79], v[78:79], 0, v[252:253]
	s_lshl_b32 s4, s13, 14
	v_lshl_add_u32 v67, v184, 2, s4
	s_lshl_b32 s4, s13, 9
	s_lshl_b32 s5, s15, 8
	s_add_i32 s4, s4, s5
	s_add_i32 s4, s4, 0x10000
	v_lshl_add_u32 v68, v184, 2, s4
	s_waitcnt lgkmcnt(0)
	v_add_f32_e32 v65, v193, v65
	v_sub_f32_e32 v66, v191, v192
	v_subrev_f32_e32 v66, s2, v66
	s_cmp_eq_u32 s15, 0
	s_cselect_b64 s[0:1], -1, 0
	s_nop 0
	v_cndmask_b32_e64 v66, v66, 1.0, s[0:1]
	v_div_scale_f32 v72, s[0:1], v65, v65, v66
	v_div_scale_f32 v74, vcc, v66, v65, v66
	v_rcp_f32_e32 v73, v72
	s_nop 0
	v_fma_f32 v75, -v72, v73, 1.0
	v_fmac_f32_e32 v73, v75, v73
	v_mul_f32_e32 v75, v74, v73
	v_fma_f32 v64, -v72, v75, v74
	v_fmac_f32_e32 v75, v64, v73
	v_fma_f32 v72, -v72, v75, v74
	v_div_fmas_f32 v72, v72, v73, v75
	v_div_fixup_f32 v64, v72, v65, v66
	v_pk_mul_f32 v[48:49], v[48:49], v[64:65] op_sel_hi:[1,0]
	v_pk_mul_f32 v[50:51], v[50:51], v[64:65] op_sel_hi:[1,0]
	v_pk_mul_f32 v[52:53], v[52:53], v[64:65] op_sel_hi:[1,0]
	v_pk_mul_f32 v[54:55], v[54:55], v[64:65] op_sel_hi:[1,0]
	v_pk_mul_f32 v[56:57], v[56:57], v[64:65] op_sel_hi:[1,0]
	v_pk_mul_f32 v[58:59], v[58:59], v[64:65] op_sel_hi:[1,0]
	v_pk_mul_f32 v[60:61], v[60:61], v[64:65] op_sel_hi:[1,0]
	v_pk_mul_f32 v[62:63], v[62:63], v[64:65] op_sel_hi:[1,0]
	v_pk_mul_f32 v[32:33], v[32:33], v[64:65] op_sel_hi:[1,0]
	v_pk_mul_f32 v[34:35], v[34:35], v[64:65] op_sel_hi:[1,0]
	v_pk_mul_f32 v[36:37], v[36:37], v[64:65] op_sel_hi:[1,0]
	v_pk_mul_f32 v[38:39], v[38:39], v[64:65] op_sel_hi:[1,0]
	v_pk_mul_f32 v[40:41], v[40:41], v[64:65] op_sel_hi:[1,0]
	v_pk_mul_f32 v[42:43], v[42:43], v[64:65] op_sel_hi:[1,0]
	v_pk_mul_f32 v[44:45], v[44:45], v[64:65] op_sel_hi:[1,0]
	v_pk_mul_f32 v[46:47], v[46:47], v[64:65] op_sel_hi:[1,0]
	v_pk_mul_f32 v[16:17], v[16:17], v[64:65] op_sel_hi:[1,0]
	v_pk_mul_f32 v[18:19], v[18:19], v[64:65] op_sel_hi:[1,0]
	v_pk_mul_f32 v[20:21], v[20:21], v[64:65] op_sel_hi:[1,0]
	v_pk_mul_f32 v[22:23], v[22:23], v[64:65] op_sel_hi:[1,0]
	v_pk_mul_f32 v[24:25], v[24:25], v[64:65] op_sel_hi:[1,0]
	v_pk_mul_f32 v[26:27], v[26:27], v[64:65] op_sel_hi:[1,0]
	v_pk_mul_f32 v[28:29], v[28:29], v[64:65] op_sel_hi:[1,0]
	v_pk_mul_f32 v[30:31], v[30:31], v[64:65] op_sel_hi:[1,0]
	v_pk_mul_f32 v[0:1], v[0:1], v[64:65] op_sel_hi:[1,0]
	v_pk_mul_f32 v[2:3], v[2:3], v[64:65] op_sel_hi:[1,0]
	v_pk_mul_f32 v[4:5], v[4:5], v[64:65] op_sel_hi:[1,0]
	v_pk_mul_f32 v[6:7], v[6:7], v[64:65] op_sel_hi:[1,0]
	v_pk_mul_f32 v[8:9], v[8:9], v[64:65] op_sel_hi:[1,0]
	v_pk_mul_f32 v[10:11], v[10:11], v[64:65] op_sel_hi:[1,0]
	v_pk_mul_f32 v[12:13], v[12:13], v[64:65] op_sel_hi:[1,0]
	v_pk_mul_f32 v[14:15], v[14:15], v[64:65] op_sel_hi:[1,0]
	s_cmp_lg_u32 s15, 0
	s_cbranch_scc1 .Ldt_c1
	ds_write2st64_b32 v67, v16, v17 offset0:32 offset1:33
	ds_write2st64_b32 v67, v18, v19 offset0:34 offset1:35
	ds_write2st64_b32 v67, v20, v21 offset0:36 offset1:37
	ds_write2st64_b32 v67, v22, v23 offset0:38 offset1:39
	ds_write2st64_b32 v67, v24, v25 offset0:40 offset1:41
	ds_write2st64_b32 v67, v26, v27 offset0:42 offset1:43
	ds_write2st64_b32 v67, v28, v29 offset0:44 offset1:45
	ds_write2st64_b32 v67, v30, v31 offset0:46 offset1:47
	ds_write2st64_b32 v67, v0, v1 offset0:48 offset1:49
	ds_write2st64_b32 v67, v2, v3 offset0:50 offset1:51
	ds_write2st64_b32 v67, v4, v5 offset0:52 offset1:53
	ds_write2st64_b32 v67, v6, v7 offset0:54 offset1:55
	ds_write2st64_b32 v67, v8, v9 offset0:56 offset1:57
	ds_write2st64_b32 v67, v10, v11 offset0:58 offset1:59
	ds_write2st64_b32 v67, v12, v13 offset0:60 offset1:61
	ds_write2st64_b32 v67, v14, v15 offset0:62 offset1:63
	s_waitcnt lgkmcnt(0)
	s_barrier
; __device__ __forceinline__ float bflo(unsigned w) { return __uint_as_float(w << 16); }
; __device__ __forceinline__ float bfhi(unsigned w) { return __uint_as_float(w & 0xffff0000u); }
; __device__ __forceinline__ float silu_f(float x) { return x / (1.0f + __expf(-x)); }
; __device__ void da_unit(char* lds, const Params& p, int layer, int unit) {
;     ...
;     if (c == 0) {
;         const float i0 = 1.0f / lsum;
;         float ss = 0.f;
; #pragma unroll
;         for (int k = 0; k < 4; ++k)
; #pragma unroll
;             for (int e = 0; e < 16; ++e) { const float a = O[k][e] * i0 - xch[(k * 16 + e) * 64 + lane]; O[k][e] = a; ss += a * a; }
;         ss += __shfl_xor(ss, 32);
;         const float rstd = rsqrtf(ss * (1.0f / 128.0f) + RMS_EPS) * (1.0f - p.lam_init[layer]);
;         const float* sg = (const float*)(lds + LDS_SG_OFF);
;         __builtin_amdgcn_sched_barrier(0);
; #pragma unroll
;         for (int k = 0; k < 4; ++k)
; #pragma unroll
;             for (int g = 0; g < 4; ++g) {
;                 const int d0 = 32 * k + 8 * g + 4 * h2;
;                 const f32x4 gg = *(const f32x4*)(sg + d0);
;                 const u32x2 gw = gwv[k * 4 + g];
;                 const float o0 = O[k][4 * g + 0] * rstd * gg[0] * silu_f(bflo(gw.x));
;                 const float o1 = O[k][4 * g + 1] * rstd * gg[1] * silu_f(bfhi(gw.x));
;                 const float o2 = O[k][4 * g + 2] * rstd * gg[2] * silu_f(bflo(gw.y));
;                 const float o3 = O[k][4 * g + 3] * rstd * gg[3] * silu_f(bfhi(gw.y));
;                 u32x2 w; w.x = cvt_pk_bf16(o0, o1); w.y = cvt_pk_bf16(o2, o3);
	ds_read2st64_b32 v[80:81], v67 offset0:0 offset1:1
	ds_read2st64_b32 v[82:83], v67 offset0:2 offset1:3
	ds_read2st64_b32 v[84:85], v67 offset0:4 offset1:5
	ds_read2st64_b32 v[86:87], v67 offset0:6 offset1:7
	ds_read2st64_b32 v[88:89], v67 offset0:8 offset1:9
	ds_read2st64_b32 v[90:91], v67 offset0:10 offset1:11
	ds_read2st64_b32 v[92:93], v67 offset0:12 offset1:13
	ds_read2st64_b32 v[94:95], v67 offset0:14 offset1:15
	s_waitcnt lgkmcnt(0)
	v_pk_add_f32 v[48:49], v[48:49], v[80:81]
	v_pk_add_f32 v[50:51], v[50:51], v[82:83]
	v_pk_add_f32 v[52:53], v[52:53], v[84:85]
	v_pk_add_f32 v[54:55], v[54:55], v[86:87]
	v_pk_add_f32 v[56:57], v[56:57], v[88:89]
	v_pk_add_f32 v[58:59], v[58:59], v[90:91]
	v_pk_add_f32 v[60:61], v[60:61], v[92:93]
	v_pk_add_f32 v[62:63], v[62:63], v[94:95]
	v_pk_mul_f32 v[76:77], v[48:49], v[48:49]
	v_pk_fma_f32 v[76:77], v[50:51], v[50:51], v[76:77]
	v_pk_fma_f32 v[76:77], v[52:53], v[52:53], v[76:77]
	v_pk_fma_f32 v[76:77], v[54:55], v[54:55], v[76:77]
	v_pk_fma_f32 v[76:77], v[56:57], v[56:57], v[76:77]
	v_pk_fma_f32 v[76:77], v[58:59], v[58:59], v[76:77]
	v_pk_fma_f32 v[76:77], v[60:61], v[60:61], v[76:77]
	v_pk_fma_f32 v[76:77], v[62:63], v[62:63], v[76:77]
	ds_read2st64_b32 v[80:81], v67 offset0:16 offset1:17
	ds_read2st64_b32 v[82:83], v67 offset0:18 offset1:19
	ds_read2st64_b32 v[84:85], v67 offset0:20 offset1:21
	ds_read2st64_b32 v[86:87], v67 offset0:22 offset1:23
	ds_read2st64_b32 v[88:89], v67 offset0:24 offset1:25
	ds_read2st64_b32 v[90:91], v67 offset0:26 offset1:27
	ds_read2st64_b32 v[92:93], v67 offset0:28 offset1:29
	ds_read2st64_b32 v[94:95], v67 offset0:30 offset1:31
	s_waitcnt lgkmcnt(0)
	v_pk_add_f32 v[32:33], v[32:33], v[80:81]
	v_pk_add_f32 v[34:35], v[34:35], v[82:83]
	v_pk_add_f32 v[36:37], v[36:37], v[84:85]
	v_pk_add_f32 v[38:39], v[38:39], v[86:87]
	v_pk_add_f32 v[40:41], v[40:41], v[88:89]
	v_pk_add_f32 v[42:43], v[42:43], v[90:91]
	v_pk_add_f32 v[44:45], v[44:45], v[92:93]
	v_pk_add_f32 v[46:47], v[46:47], v[94:95]
	v_pk_fma_f32 v[76:77], v[32:33], v[32:33], v[76:77]
	v_pk_fma_f32 v[76:77], v[34:35], v[34:35], v[76:77]
	v_pk_fma_f32 v[76:77], v[36:37], v[36:37], v[76:77]
	v_pk_fma_f32 v[76:77], v[38:39], v[38:39], v[76:77]
	v_pk_fma_f32 v[76:77], v[40:41], v[40:41], v[76:77]
	v_pk_fma_f32 v[76:77], v[42:43], v[42:43], v[76:77]
	v_pk_fma_f32 v[76:77], v[44:45], v[44:45], v[76:77]
	v_pk_fma_f32 v[76:77], v[46:47], v[46:47], v[76:77]
	v_add_f32_e32 v69, v76, v77
	ds_bpermute_b32 v72, v244, v69
	s_waitcnt lgkmcnt(0)
	v_add_f32_e32 v69, v69, v72
	ds_write_b32 v68, v69
	s_waitcnt lgkmcnt(0)
	s_barrier
	ds_read_b32 v72, v68 offset:256
	v_mov_b32_e32 v74, 0x358637bd
	v_sub_f32_e64 v75, 1.0, s2
	s_waitcnt lgkmcnt(0)
	v_add_f32_e32 v69, v69, v72
	v_fmamk_f32 v69, v69, 0x3c000000, v74
	v_rsq_f32_e32 v69, v69
	s_nop 0
	v_mul_f32_e32 v70, v75, v69
	v_lshl_add_u32 v72, v188, 4, 0
	v_add_u32_e32 v72, 0x26b30, v72
	s_waitcnt vmcnt(0)
	s_mov_b32 s16, 0xbfb8aa3b
	s_mov_b32 s18, 1.0
	ds_read_b128 v[216:219], v72 offset:0
	v_lshlrev_b32_e32 v96, 16, v200
	v_and_b32_e32 v97, 0xffff0000, v200
	v_lshlrev_b32_e32 v98, 16, v201
	v_and_b32_e32 v99, 0xffff0000, v201
	v_pk_mul_f32 v[104:105], v[96:97], s[16:17] op_sel_hi:[1,0]
	v_pk_mul_f32 v[106:107], v[98:99], s[16:17] op_sel_hi:[1,0]
	v_exp_f32_e32 v104, v104
	v_exp_f32_e32 v105, v105
	v_exp_f32_e32 v106, v106
	v_exp_f32_e32 v107, v107
	v_pk_add_f32 v[104:105], v[104:105], s[18:19] op_sel_hi:[1,0]
	v_pk_add_f32 v[106:107], v[106:107], s[18:19] op_sel_hi:[1,0]
	v_div_scale_f32 v108, s[0:1], v104, v104, v96
	v_div_scale_f32 v109, s[0:1], v105, v105, v97
	v_div_scale_f32 v110, s[0:1], v106, v106, v98
	v_div_scale_f32 v111, s[0:1], v107, v107, v99
	v_rcp_f32_e32 v112, v108
	v_rcp_f32_e32 v113, v109
	v_rcp_f32_e32 v114, v110
	v_rcp_f32_e32 v115, v111
	v_pk_fma_f32 v[100:101], v[108:109], v[112:113], s[18:19] op_sel_hi:[1,1,0] neg_lo:[1,0,0] neg_hi:[1,0,0]
	v_pk_fma_f32 v[102:103], v[110:111], v[114:115], s[18:19] op_sel_hi:[1,1,0] neg_lo:[1,0,0] neg_hi:[1,0,0]
	v_pk_fma_f32 v[112:113], v[100:101], v[112:113], v[112:113]
	v_pk_fma_f32 v[114:115], v[102:103], v[114:115], v[114:115]
	v_div_scale_f32 v116, s[2:3], v96, v104, v96
	v_div_scale_f32 v117, vcc, v97, v105, v97
	v_pk_mul_f32 v[100:101], v[116:117], v[112:113]
	v_pk_fma_f32 v[120:121], v[108:109], v[100:101], v[116:117] neg_lo:[1,0,0] neg_hi:[1,0,0]
	v_pk_fma_f32 v[100:101], v[120:121], v[112:113], v[100:101]
	v_pk_fma_f32 v[120:121], v[108:109], v[100:101], v[116:117] neg_lo:[1,0,0] neg_hi:[1,0,0]
	v_div_fmas_f32 v121, v121, v113, v101
	v_div_fixup_f32 v101, v121, v105, v97
	s_mov_b64 vcc, s[2:3]
	s_nop 1
	v_div_fmas_f32 v120, v120, v112, v100
	v_div_fixup_f32 v100, v120, v104, v96
	v_div_scale_f32 v118, s[2:3], v98, v106, v98
	v_div_scale_f32 v119, vcc, v99, v107, v99
	v_pk_mul_f32 v[102:103], v[118:119], v[114:115]
	v_pk_fma_f32 v[122:123], v[110:111], v[102:103], v[118:119] neg_lo:[1,0,0] neg_hi:[1,0,0]
	v_pk_fma_f32 v[102:103], v[122:123], v[114:115], v[102:103]
	v_pk_fma_f32 v[122:123], v[110:111], v[102:103], v[118:119] neg_lo:[1,0,0] neg_hi:[1,0,0]
	v_div_fmas_f32 v123, v123, v115, v103
	v_div_fixup_f32 v103, v123, v107, v99
	s_mov_b64 vcc, s[2:3]
	s_nop 1
	v_div_fmas_f32 v122, v122, v114, v102
	v_div_fixup_f32 v102, v122, v106, v98
	s_waitcnt lgkmcnt(0)
; __device__ __forceinline__ float bflo(unsigned w) { return __uint_as_float(w << 16); }
; __device__ __forceinline__ float bfhi(unsigned w) { return __uint_as_float(w & 0xffff0000u); }
; __device__ __forceinline__ float silu_f(float x) { return x / (1.0f + __expf(-x)); }
; __device__ void da_unit(char* lds, const Params& p, int layer, int unit) {
;     ...
;             for (int g = 0; g < 4; ++g) {
;                 const int d0 = 32 * k + 8 * g + 4 * h2;
;                 const f32x4 gg = *(const f32x4*)(sg + d0);
;                 const u32x2 gw = gwv[k * 4 + g];
;                 const float o0 = O[k][4 * g + 0] * rstd * gg[0] * silu_f(bflo(gw.x));
;                 const float o1 = O[k][4 * g + 1] * rstd * gg[1] * silu_f(bfhi(gw.x));
;                 const float o2 = O[k][4 * g + 2] * rstd * gg[2] * silu_f(bflo(gw.y));
;                 const float o3 = O[k][4 * g + 3] * rstd * gg[3] * silu_f(bfhi(gw.y));
;                 u32x2 w; w.x = cvt_pk_bf16(o0, o1); w.y = cvt_pk_bf16(o2, o3);
;                 *(u32x2*)(p.o + tokq * 1024 + h * 128 + d0) = w;
;             }
	v_pk_mul_f32 v[48:49], v[48:49], v[70:71] op_sel_hi:[1,0]
	v_pk_mul_f32 v[48:49], v[48:49], v[216:217]
	v_pk_mul_f32 v[48:49], v[48:49], v[100:101]
	v_pk_mul_f32 v[50:51], v[50:51], v[70:71] op_sel_hi:[1,0]
	v_pk_mul_f32 v[50:51], v[50:51], v[218:219]
	v_pk_mul_f32 v[50:51], v[50:51], v[102:103]
	v_cvt_pk_bf16_f32 v96, v48, v49
	v_cvt_pk_bf16_f32 v97, v50, v51
	global_store_dwordx2 v[78:79], v[96:97], off offset:0
	ds_read_b128 v[216:219], v72 offset:32
	v_lshlrev_b32_e32 v96, 16, v202
	v_and_b32_e32 v97, 0xffff0000, v202
	v_lshlrev_b32_e32 v98, 16, v203
	v_and_b32_e32 v99, 0xffff0000, v203
	v_pk_mul_f32 v[104:105], v[96:97], s[16:17] op_sel_hi:[1,0]
	v_pk_mul_f32 v[106:107], v[98:99], s[16:17] op_sel_hi:[1,0]
	v_exp_f32_e32 v104, v104
	v_exp_f32_e32 v105, v105
	v_exp_f32_e32 v106, v106
	v_exp_f32_e32 v107, v107
	v_pk_add_f32 v[104:105], v[104:105], s[18:19] op_sel_hi:[1,0]
	v_pk_add_f32 v[106:107], v[106:107], s[18:19] op_sel_hi:[1,0]
	v_div_scale_f32 v108, s[0:1], v104, v104, v96
	v_div_scale_f32 v109, s[0:1], v105, v105, v97
	v_div_scale_f32 v110, s[0:1], v106, v106, v98
	v_div_scale_f32 v111, s[0:1], v107, v107, v99
	v_rcp_f32_e32 v112, v108
	v_rcp_f32_e32 v113, v109
	v_rcp_f32_e32 v114, v110
	v_rcp_f32_e32 v115, v111
	v_pk_fma_f32 v[100:101], v[108:109], v[112:113], s[18:19] op_sel_hi:[1,1,0] neg_lo:[1,0,0] neg_hi:[1,0,0]
	v_pk_fma_f32 v[102:103], v[110:111], v[114:115], s[18:19] op_sel_hi:[1,1,0] neg_lo:[1,0,0] neg_hi:[1,0,0]
	v_pk_fma_f32 v[112:113], v[100:101], v[112:113], v[112:113]
	v_pk_fma_f32 v[114:115], v[102:103], v[114:115], v[114:115]
	v_div_scale_f32 v116, s[2:3], v96, v104, v96
	v_div_scale_f32 v117, vcc, v97, v105, v97
	v_pk_mul_f32 v[100:101], v[116:117], v[112:113]
	v_pk_fma_f32 v[120:121], v[108:109], v[100:101], v[116:117] neg_lo:[1,0,0] neg_hi:[1,0,0]
	v_pk_fma_f32 v[100:101], v[120:121], v[112:113], v[100:101]
	v_pk_fma_f32 v[120:121], v[108:109], v[100:101], v[116:117] neg_lo:[1,0,0] neg_hi:[1,0,0]
	v_div_fmas_f32 v121, v121, v113, v101
	v_div_fixup_f32 v101, v121, v105, v97
	s_mov_b64 vcc, s[2:3]
	s_nop 1
	v_div_fmas_f32 v120, v120, v112, v100
	v_div_fixup_f32 v100, v120, v104, v96
	v_div_scale_f32 v118, s[2:3], v98, v106, v98
	v_div_scale_f32 v119, vcc, v99, v107, v99
	v_pk_mul_f32 v[102:103], v[118:119], v[114:115]
	v_pk_fma_f32 v[122:123], v[110:111], v[102:103], v[118:119] neg_lo:[1,0,0] neg_hi:[1,0,0]
	v_pk_fma_f32 v[102:103], v[122:123], v[114:115], v[102:103]
	v_pk_fma_f32 v[122:123], v[110:111], v[102:103], v[118:119] neg_lo:[1,0,0] neg_hi:[1,0,0]
	v_div_fmas_f32 v123, v123, v115, v103
	v_div_fixup_f32 v103, v123, v107, v99
	s_mov_b64 vcc, s[2:3]
	s_nop 1
	v_div_fmas_f32 v122, v122, v114, v102
	v_div_fixup_f32 v102, v122, v106, v98
	s_waitcnt lgkmcnt(0)
	v_pk_mul_f32 v[52:53], v[52:53], v[70:71] op_sel_hi:[1,0]
	v_pk_mul_f32 v[52:53], v[52:53], v[216:217]
	v_pk_mul_f32 v[52:53], v[52:53], v[100:101]
	v_pk_mul_f32 v[54:55], v[54:55], v[70:71] op_sel_hi:[1,0]
	v_pk_mul_f32 v[54:55], v[54:55], v[218:219]
	v_pk_mul_f32 v[54:55], v[54:55], v[102:103]
	v_cvt_pk_bf16_f32 v96, v52, v53
	v_cvt_pk_bf16_f32 v97, v54, v55
	global_store_dwordx2 v[78:79], v[96:97], off offset:16
	ds_read_b128 v[216:219], v72 offset:64
	v_lshlrev_b32_e32 v96, 16, v204
	v_and_b32_e32 v97, 0xffff0000, v204
	v_lshlrev_b32_e32 v98, 16, v205
	v_and_b32_e32 v99, 0xffff0000, v205
	v_pk_mul_f32 v[104:105], v[96:97], s[16:17] op_sel_hi:[1,0]
	v_pk_mul_f32 v[106:107], v[98:99], s[16:17] op_sel_hi:[1,0]
	v_exp_f32_e32 v104, v104
	v_exp_f32_e32 v105, v105
	v_exp_f32_e32 v106, v106
	v_exp_f32_e32 v107, v107
	v_pk_add_f32 v[104:105], v[104:105], s[18:19] op_sel_hi:[1,0]
	v_pk_add_f32 v[106:107], v[106:107], s[18:19] op_sel_hi:[1,0]
	v_div_scale_f32 v108, s[0:1], v104, v104, v96
	v_div_scale_f32 v109, s[0:1], v105, v105, v97
	v_div_scale_f32 v110, s[0:1], v106, v106, v98
	v_div_scale_f32 v111, s[0:1], v107, v107, v99
	v_rcp_f32_e32 v112, v108
	v_rcp_f32_e32 v113, v109
	v_rcp_f32_e32 v114, v110
	v_rcp_f32_e32 v115, v111
	v_pk_fma_f32 v[100:101], v[108:109], v[112:113], s[18:19] op_sel_hi:[1,1,0] neg_lo:[1,0,0] neg_hi:[1,0,0]
	v_pk_fma_f32 v[102:103], v[110:111], v[114:115], s[18:19] op_sel_hi:[1,1,0] neg_lo:[1,0,0] neg_hi:[1,0,0]
	v_pk_fma_f32 v[112:113], v[100:101], v[112:113], v[112:113]
	v_pk_fma_f32 v[114:115], v[102:103], v[114:115], v[114:115]
	v_div_scale_f32 v116, s[2:3], v96, v104, v96
	v_div_scale_f32 v117, vcc, v97, v105, v97
	v_pk_mul_f32 v[100:101], v[116:117], v[112:113]
	v_pk_fma_f32 v[120:121], v[108:109], v[100:101], v[116:117] neg_lo:[1,0,0] neg_hi:[1,0,0]
	v_pk_fma_f32 v[100:101], v[120:121], v[112:113], v[100:101]
	v_pk_fma_f32 v[120:121], v[108:109], v[100:101], v[116:117] neg_lo:[1,0,0] neg_hi:[1,0,0]
	v_div_fmas_f32 v121, v121, v113, v101
	v_div_fixup_f32 v101, v121, v105, v97
	s_mov_b64 vcc, s[2:3]
	s_nop 1
	v_div_fmas_f32 v120, v120, v112, v100
	v_div_fixup_f32 v100, v120, v104, v96
	v_div_scale_f32 v118, s[2:3], v98, v106, v98
	v_div_scale_f32 v119, vcc, v99, v107, v99
	v_pk_mul_f32 v[102:103], v[118:119], v[114:115]
	v_pk_fma_f32 v[122:123], v[110:111], v[102:103], v[118:119] neg_lo:[1,0,0] neg_hi:[1,0,0]
	v_pk_fma_f32 v[102:103], v[122:123], v[114:115], v[102:103]
	v_pk_fma_f32 v[122:123], v[110:111], v[102:103], v[118:119] neg_lo:[1,0,0] neg_hi:[1,0,0]
	v_div_fmas_f32 v123, v123, v115, v103
	v_div_fixup_f32 v103, v123, v107, v99
	s_mov_b64 vcc, s[2:3]
	s_nop 1
	v_div_fmas_f32 v122, v122, v114, v102
	v_div_fixup_f32 v102, v122, v106, v98
	s_waitcnt lgkmcnt(0)
; __device__ __forceinline__ float bflo(unsigned w) { return __uint_as_float(w << 16); }
; __device__ __forceinline__ float bfhi(unsigned w) { return __uint_as_float(w & 0xffff0000u); }
; __device__ __forceinline__ float silu_f(float x) { return x / (1.0f + __expf(-x)); }
; __device__ void da_unit(char* lds, const Params& p, int layer, int unit) {
;     ...
;             for (int g = 0; g < 4; ++g) {
;                 const int d0 = 32 * k + 8 * g + 4 * h2;
;                 const f32x4 gg = *(const f32x4*)(sg + d0);
;                 const u32x2 gw = gwv[k * 4 + g];
;                 const float o0 = O[k][4 * g + 0] * rstd * gg[0] * silu_f(bflo(gw.x));
;                 const float o1 = O[k][4 * g + 1] * rstd * gg[1] * silu_f(bfhi(gw.x));
;                 const float o2 = O[k][4 * g + 2] * rstd * gg[2] * silu_f(bflo(gw.y));
;                 const float o3 = O[k][4 * g + 3] * rstd * gg[3] * silu_f(bfhi(gw.y));
;                 u32x2 w; w.x = cvt_pk_bf16(o0, o1); w.y = cvt_pk_bf16(o2, o3);
;                 *(u32x2*)(p.o + tokq * 1024 + h * 128 + d0) = w;
;             }
	v_pk_mul_f32 v[56:57], v[56:57], v[70:71] op_sel_hi:[1,0]
	v_pk_mul_f32 v[56:57], v[56:57], v[216:217]
	v_pk_mul_f32 v[56:57], v[56:57], v[100:101]
	v_pk_mul_f32 v[58:59], v[58:59], v[70:71] op_sel_hi:[1,0]
	v_pk_mul_f32 v[58:59], v[58:59], v[218:219]
	v_pk_mul_f32 v[58:59], v[58:59], v[102:103]
	v_cvt_pk_bf16_f32 v96, v56, v57
	v_cvt_pk_bf16_f32 v97, v58, v59
	global_store_dwordx2 v[78:79], v[96:97], off offset:32
	ds_read_b128 v[216:219], v72 offset:96
	v_lshlrev_b32_e32 v96, 16, v206
	v_and_b32_e32 v97, 0xffff0000, v206
	v_lshlrev_b32_e32 v98, 16, v207
	v_and_b32_e32 v99, 0xffff0000, v207
	v_pk_mul_f32 v[104:105], v[96:97], s[16:17] op_sel_hi:[1,0]
	v_pk_mul_f32 v[106:107], v[98:99], s[16:17] op_sel_hi:[1,0]
	v_exp_f32_e32 v104, v104
	v_exp_f32_e32 v105, v105
	v_exp_f32_e32 v106, v106
	v_exp_f32_e32 v107, v107
	v_pk_add_f32 v[104:105], v[104:105], s[18:19] op_sel_hi:[1,0]
	v_pk_add_f32 v[106:107], v[106:107], s[18:19] op_sel_hi:[1,0]
	v_div_scale_f32 v108, s[0:1], v104, v104, v96
	v_div_scale_f32 v109, s[0:1], v105, v105, v97
	v_div_scale_f32 v110, s[0:1], v106, v106, v98
	v_div_scale_f32 v111, s[0:1], v107, v107, v99
	v_rcp_f32_e32 v112, v108
	v_rcp_f32_e32 v113, v109
	v_rcp_f32_e32 v114, v110
	v_rcp_f32_e32 v115, v111
	v_pk_fma_f32 v[100:101], v[108:109], v[112:113], s[18:19] op_sel_hi:[1,1,0] neg_lo:[1,0,0] neg_hi:[1,0,0]
	v_pk_fma_f32 v[102:103], v[110:111], v[114:115], s[18:19] op_sel_hi:[1,1,0] neg_lo:[1,0,0] neg_hi:[1,0,0]
	v_pk_fma_f32 v[112:113], v[100:101], v[112:113], v[112:113]
	v_pk_fma_f32 v[114:115], v[102:103], v[114:115], v[114:115]
	v_div_scale_f32 v116, s[2:3], v96, v104, v96
	v_div_scale_f32 v117, vcc, v97, v105, v97
	v_pk_mul_f32 v[100:101], v[116:117], v[112:113]
	v_pk_fma_f32 v[120:121], v[108:109], v[100:101], v[116:117] neg_lo:[1,0,0] neg_hi:[1,0,0]
	v_pk_fma_f32 v[100:101], v[120:121], v[112:113], v[100:101]
	v_pk_fma_f32 v[120:121], v[108:109], v[100:101], v[116:117] neg_lo:[1,0,0] neg_hi:[1,0,0]
	v_div_fmas_f32 v121, v121, v113, v101
	v_div_fixup_f32 v101, v121, v105, v97
	s_mov_b64 vcc, s[2:3]
	s_nop 1
	v_div_fmas_f32 v120, v120, v112, v100
	v_div_fixup_f32 v100, v120, v104, v96
	v_div_scale_f32 v118, s[2:3], v98, v106, v98
	v_div_scale_f32 v119, vcc, v99, v107, v99
	v_pk_mul_f32 v[102:103], v[118:119], v[114:115]
	v_pk_fma_f32 v[122:123], v[110:111], v[102:103], v[118:119] neg_lo:[1,0,0] neg_hi:[1,0,0]
	v_pk_fma_f32 v[102:103], v[122:123], v[114:115], v[102:103]
	v_pk_fma_f32 v[122:123], v[110:111], v[102:103], v[118:119] neg_lo:[1,0,0] neg_hi:[1,0,0]
	v_div_fmas_f32 v123, v123, v115, v103
	v_div_fixup_f32 v103, v123, v107, v99
	s_mov_b64 vcc, s[2:3]
	s_nop 1
	v_div_fmas_f32 v122, v122, v114, v102
	v_div_fixup_f32 v102, v122, v106, v98
	s_waitcnt lgkmcnt(0)
	v_pk_mul_f32 v[60:61], v[60:61], v[70:71] op_sel_hi:[1,0]
	v_pk_mul_f32 v[60:61], v[60:61], v[216:217]
	v_pk_mul_f32 v[60:61], v[60:61], v[100:101]
	v_pk_mul_f32 v[62:63], v[62:63], v[70:71] op_sel_hi:[1,0]
	v_pk_mul_f32 v[62:63], v[62:63], v[218:219]
	v_pk_mul_f32 v[62:63], v[62:63], v[102:103]
	v_cvt_pk_bf16_f32 v96, v60, v61
	v_cvt_pk_bf16_f32 v97, v62, v63
	global_store_dwordx2 v[78:79], v[96:97], off offset:48
	ds_read_b128 v[216:219], v72 offset:128
	v_lshlrev_b32_e32 v96, 16, v208
	v_and_b32_e32 v97, 0xffff0000, v208
	v_lshlrev_b32_e32 v98, 16, v209
	v_and_b32_e32 v99, 0xffff0000, v209
	v_pk_mul_f32 v[104:105], v[96:97], s[16:17] op_sel_hi:[1,0]
	v_pk_mul_f32 v[106:107], v[98:99], s[16:17] op_sel_hi:[1,0]
	v_exp_f32_e32 v104, v104
	v_exp_f32_e32 v105, v105
	v_exp_f32_e32 v106, v106
	v_exp_f32_e32 v107, v107
	v_pk_add_f32 v[104:105], v[104:105], s[18:19] op_sel_hi:[1,0]
	v_pk_add_f32 v[106:107], v[106:107], s[18:19] op_sel_hi:[1,0]
	v_div_scale_f32 v108, s[0:1], v104, v104, v96
	v_div_scale_f32 v109, s[0:1], v105, v105, v97
	v_div_scale_f32 v110, s[0:1], v106, v106, v98
	v_div_scale_f32 v111, s[0:1], v107, v107, v99
	v_rcp_f32_e32 v112, v108
	v_rcp_f32_e32 v113, v109
	v_rcp_f32_e32 v114, v110
	v_rcp_f32_e32 v115, v111
	v_pk_fma_f32 v[100:101], v[108:109], v[112:113], s[18:19] op_sel_hi:[1,1,0] neg_lo:[1,0,0] neg_hi:[1,0,0]
	v_pk_fma_f32 v[102:103], v[110:111], v[114:115], s[18:19] op_sel_hi:[1,1,0] neg_lo:[1,0,0] neg_hi:[1,0,0]
	v_pk_fma_f32 v[112:113], v[100:101], v[112:113], v[112:113]
	v_pk_fma_f32 v[114:115], v[102:103], v[114:115], v[114:115]
	v_div_scale_f32 v116, s[2:3], v96, v104, v96
	v_div_scale_f32 v117, vcc, v97, v105, v97
	v_pk_mul_f32 v[100:101], v[116:117], v[112:113]
	v_pk_fma_f32 v[120:121], v[108:109], v[100:101], v[116:117] neg_lo:[1,0,0] neg_hi:[1,0,0]
	v_pk_fma_f32 v[100:101], v[120:121], v[112:113], v[100:101]
	v_pk_fma_f32 v[120:121], v[108:109], v[100:101], v[116:117] neg_lo:[1,0,0] neg_hi:[1,0,0]
	v_div_fmas_f32 v121, v121, v113, v101
	v_div_fixup_f32 v101, v121, v105, v97
	s_mov_b64 vcc, s[2:3]
	s_nop 1
	v_div_fmas_f32 v120, v120, v112, v100
	v_div_fixup_f32 v100, v120, v104, v96
	v_div_scale_f32 v118, s[2:3], v98, v106, v98
	v_div_scale_f32 v119, vcc, v99, v107, v99
	v_pk_mul_f32 v[102:103], v[118:119], v[114:115]
	v_pk_fma_f32 v[122:123], v[110:111], v[102:103], v[118:119] neg_lo:[1,0,0] neg_hi:[1,0,0]
	v_pk_fma_f32 v[102:103], v[122:123], v[114:115], v[102:103]
	v_pk_fma_f32 v[122:123], v[110:111], v[102:103], v[118:119] neg_lo:[1,0,0] neg_hi:[1,0,0]
	v_div_fmas_f32 v123, v123, v115, v103
	v_div_fixup_f32 v103, v123, v107, v99
	s_mov_b64 vcc, s[2:3]
	s_nop 1
	v_div_fmas_f32 v122, v122, v114, v102
	v_div_fixup_f32 v102, v122, v106, v98
	s_waitcnt lgkmcnt(0)
; __device__ __forceinline__ float bflo(unsigned w) { return __uint_as_float(w << 16); }
; __device__ __forceinline__ float bfhi(unsigned w) { return __uint_as_float(w & 0xffff0000u); }
; __device__ __forceinline__ float silu_f(float x) { return x / (1.0f + __expf(-x)); }
; __device__ void da_unit(char* lds, const Params& p, int layer, int unit) {
;     ...
;             for (int g = 0; g < 4; ++g) {
;                 const int d0 = 32 * k + 8 * g + 4 * h2;
;                 const f32x4 gg = *(const f32x4*)(sg + d0);
;                 const u32x2 gw = gwv[k * 4 + g];
;                 const float o0 = O[k][4 * g + 0] * rstd * gg[0] * silu_f(bflo(gw.x));
;                 const float o1 = O[k][4 * g + 1] * rstd * gg[1] * silu_f(bfhi(gw.x));
;                 const float o2 = O[k][4 * g + 2] * rstd * gg[2] * silu_f(bflo(gw.y));
;                 const float o3 = O[k][4 * g + 3] * rstd * gg[3] * silu_f(bfhi(gw.y));
;                 u32x2 w; w.x = cvt_pk_bf16(o0, o1); w.y = cvt_pk_bf16(o2, o3);
;                 *(u32x2*)(p.o + tokq * 1024 + h * 128 + d0) = w;
;             }
	v_pk_mul_f32 v[32:33], v[32:33], v[70:71] op_sel_hi:[1,0]
	v_pk_mul_f32 v[32:33], v[32:33], v[216:217]
	v_pk_mul_f32 v[32:33], v[32:33], v[100:101]
	v_pk_mul_f32 v[34:35], v[34:35], v[70:71] op_sel_hi:[1,0]
	v_pk_mul_f32 v[34:35], v[34:35], v[218:219]
	v_pk_mul_f32 v[34:35], v[34:35], v[102:103]
	v_cvt_pk_bf16_f32 v96, v32, v33
	v_cvt_pk_bf16_f32 v97, v34, v35
	global_store_dwordx2 v[78:79], v[96:97], off offset:64
	ds_read_b128 v[216:219], v72 offset:160
	v_lshlrev_b32_e32 v96, 16, v210
	v_and_b32_e32 v97, 0xffff0000, v210
	v_lshlrev_b32_e32 v98, 16, v211
	v_and_b32_e32 v99, 0xffff0000, v211
	v_pk_mul_f32 v[104:105], v[96:97], s[16:17] op_sel_hi:[1,0]
	v_pk_mul_f32 v[106:107], v[98:99], s[16:17] op_sel_hi:[1,0]
	v_exp_f32_e32 v104, v104
	v_exp_f32_e32 v105, v105
	v_exp_f32_e32 v106, v106
	v_exp_f32_e32 v107, v107
	v_pk_add_f32 v[104:105], v[104:105], s[18:19] op_sel_hi:[1,0]
	v_pk_add_f32 v[106:107], v[106:107], s[18:19] op_sel_hi:[1,0]
	v_div_scale_f32 v108, s[0:1], v104, v104, v96
	v_div_scale_f32 v109, s[0:1], v105, v105, v97
	v_div_scale_f32 v110, s[0:1], v106, v106, v98
	v_div_scale_f32 v111, s[0:1], v107, v107, v99
	v_rcp_f32_e32 v112, v108
	v_rcp_f32_e32 v113, v109
	v_rcp_f32_e32 v114, v110
	v_rcp_f32_e32 v115, v111
	v_pk_fma_f32 v[100:101], v[108:109], v[112:113], s[18:19] op_sel_hi:[1,1,0] neg_lo:[1,0,0] neg_hi:[1,0,0]
	v_pk_fma_f32 v[102:103], v[110:111], v[114:115], s[18:19] op_sel_hi:[1,1,0] neg_lo:[1,0,0] neg_hi:[1,0,0]
	v_pk_fma_f32 v[112:113], v[100:101], v[112:113], v[112:113]
	v_pk_fma_f32 v[114:115], v[102:103], v[114:115], v[114:115]
	v_div_scale_f32 v116, s[2:3], v96, v104, v96
	v_div_scale_f32 v117, vcc, v97, v105, v97
	v_pk_mul_f32 v[100:101], v[116:117], v[112:113]
	v_pk_fma_f32 v[120:121], v[108:109], v[100:101], v[116:117] neg_lo:[1,0,0] neg_hi:[1,0,0]
	v_pk_fma_f32 v[100:101], v[120:121], v[112:113], v[100:101]
	v_pk_fma_f32 v[120:121], v[108:109], v[100:101], v[116:117] neg_lo:[1,0,0] neg_hi:[1,0,0]
	v_div_fmas_f32 v121, v121, v113, v101
	v_div_fixup_f32 v101, v121, v105, v97
	s_mov_b64 vcc, s[2:3]
	s_nop 1
	v_div_fmas_f32 v120, v120, v112, v100
	v_div_fixup_f32 v100, v120, v104, v96
	v_div_scale_f32 v118, s[2:3], v98, v106, v98
	v_div_scale_f32 v119, vcc, v99, v107, v99
	v_pk_mul_f32 v[102:103], v[118:119], v[114:115]
	v_pk_fma_f32 v[122:123], v[110:111], v[102:103], v[118:119] neg_lo:[1,0,0] neg_hi:[1,0,0]
	v_pk_fma_f32 v[102:103], v[122:123], v[114:115], v[102:103]
	v_pk_fma_f32 v[122:123], v[110:111], v[102:103], v[118:119] neg_lo:[1,0,0] neg_hi:[1,0,0]
	v_div_fmas_f32 v123, v123, v115, v103
	v_div_fixup_f32 v103, v123, v107, v99
	s_mov_b64 vcc, s[2:3]
	s_nop 1
	v_div_fmas_f32 v122, v122, v114, v102
	v_div_fixup_f32 v102, v122, v106, v98
	s_waitcnt lgkmcnt(0)
	v_pk_mul_f32 v[36:37], v[36:37], v[70:71] op_sel_hi:[1,0]
	v_pk_mul_f32 v[36:37], v[36:37], v[216:217]
	v_pk_mul_f32 v[36:37], v[36:37], v[100:101]
	v_pk_mul_f32 v[38:39], v[38:39], v[70:71] op_sel_hi:[1,0]
	v_pk_mul_f32 v[38:39], v[38:39], v[218:219]
	v_pk_mul_f32 v[38:39], v[38:39], v[102:103]
	v_cvt_pk_bf16_f32 v96, v36, v37
	v_cvt_pk_bf16_f32 v97, v38, v39
	global_store_dwordx2 v[78:79], v[96:97], off offset:80
	ds_read_b128 v[216:219], v72 offset:192
	v_lshlrev_b32_e32 v96, 16, v212
	v_and_b32_e32 v97, 0xffff0000, v212
	v_lshlrev_b32_e32 v98, 16, v213
	v_and_b32_e32 v99, 0xffff0000, v213
	v_pk_mul_f32 v[104:105], v[96:97], s[16:17] op_sel_hi:[1,0]
	v_pk_mul_f32 v[106:107], v[98:99], s[16:17] op_sel_hi:[1,0]
	v_exp_f32_e32 v104, v104
	v_exp_f32_e32 v105, v105
	v_exp_f32_e32 v106, v106
	v_exp_f32_e32 v107, v107
	v_pk_add_f32 v[104:105], v[104:105], s[18:19] op_sel_hi:[1,0]
	v_pk_add_f32 v[106:107], v[106:107], s[18:19] op_sel_hi:[1,0]
	v_div_scale_f32 v108, s[0:1], v104, v104, v96
	v_div_scale_f32 v109, s[0:1], v105, v105, v97
	v_div_scale_f32 v110, s[0:1], v106, v106, v98
	v_div_scale_f32 v111, s[0:1], v107, v107, v99
	v_rcp_f32_e32 v112, v108
	v_rcp_f32_e32 v113, v109
	v_rcp_f32_e32 v114, v110
	v_rcp_f32_e32 v115, v111
	v_pk_fma_f32 v[100:101], v[108:109], v[112:113], s[18:19] op_sel_hi:[1,1,0] neg_lo:[1,0,0] neg_hi:[1,0,0]
	v_pk_fma_f32 v[102:103], v[110:111], v[114:115], s[18:19] op_sel_hi:[1,1,0] neg_lo:[1,0,0] neg_hi:[1,0,0]
	v_pk_fma_f32 v[112:113], v[100:101], v[112:113], v[112:113]
	v_pk_fma_f32 v[114:115], v[102:103], v[114:115], v[114:115]
	v_div_scale_f32 v116, s[2:3], v96, v104, v96
	v_div_scale_f32 v117, vcc, v97, v105, v97
	v_pk_mul_f32 v[100:101], v[116:117], v[112:113]
	v_pk_fma_f32 v[120:121], v[108:109], v[100:101], v[116:117] neg_lo:[1,0,0] neg_hi:[1,0,0]
	v_pk_fma_f32 v[100:101], v[120:121], v[112:113], v[100:101]
	v_pk_fma_f32 v[120:121], v[108:109], v[100:101], v[116:117] neg_lo:[1,0,0] neg_hi:[1,0,0]
	v_div_fmas_f32 v121, v121, v113, v101
	v_div_fixup_f32 v101, v121, v105, v97
	s_mov_b64 vcc, s[2:3]
	s_nop 1
	v_div_fmas_f32 v120, v120, v112, v100
	v_div_fixup_f32 v100, v120, v104, v96
	v_div_scale_f32 v118, s[2:3], v98, v106, v98
	v_div_scale_f32 v119, vcc, v99, v107, v99
	v_pk_mul_f32 v[102:103], v[118:119], v[114:115]
	v_pk_fma_f32 v[122:123], v[110:111], v[102:103], v[118:119] neg_lo:[1,0,0] neg_hi:[1,0,0]
	v_pk_fma_f32 v[102:103], v[122:123], v[114:115], v[102:103]
	v_pk_fma_f32 v[122:123], v[110:111], v[102:103], v[118:119] neg_lo:[1,0,0] neg_hi:[1,0,0]
	v_div_fmas_f32 v123, v123, v115, v103
	v_div_fixup_f32 v103, v123, v107, v99
	s_mov_b64 vcc, s[2:3]
	s_nop 1
	v_div_fmas_f32 v122, v122, v114, v102
	v_div_fixup_f32 v102, v122, v106, v98
	s_waitcnt lgkmcnt(0)
; __device__ __forceinline__ float bflo(unsigned w) { return __uint_as_float(w << 16); }
; __device__ __forceinline__ float bfhi(unsigned w) { return __uint_as_float(w & 0xffff0000u); }
; __device__ __forceinline__ float silu_f(float x) { return x / (1.0f + __expf(-x)); }
; __device__ void da_unit(char* lds, const Params& p, int layer, int unit) {
;     ...
;             for (int e = 0; e < 16; ++e) { const float a = O[k][e] * i0 - xch[(k * 16 + e) * 64 + lane]; O[k][e] = a; ss += a * a; }
;         ss += __shfl_xor(ss, 32);
;         const float rstd = rsqrtf(ss * (1.0f / 128.0f) + RMS_EPS) * (1.0f - p.lam_init[layer]);
;         const float* sg = (const float*)(lds + LDS_SG_OFF);
;         __builtin_amdgcn_sched_barrier(0);
; #pragma unroll
;         for (int k = 0; k < 4; ++k)
; #pragma unroll
;             for (int g = 0; g < 4; ++g) {
;                 const int d0 = 32 * k + 8 * g + 4 * h2;
;                 const f32x4 gg = *(const f32x4*)(sg + d0);
;                 const u32x2 gw = gwv[k * 4 + g];
;                 const float o0 = O[k][4 * g + 0] * rstd * gg[0] * silu_f(bflo(gw.x));
;                 const float o1 = O[k][4 * g + 1] * rstd * gg[1] * silu_f(bfhi(gw.x));
;                 const float o2 = O[k][4 * g + 2] * rstd * gg[2] * silu_f(bflo(gw.y));
;                 const float o3 = O[k][4 * g + 3] * rstd * gg[3] * silu_f(bfhi(gw.y));
;                 u32x2 w; w.x = cvt_pk_bf16(o0, o1); w.y = cvt_pk_bf16(o2, o3);
;                 *(u32x2*)(p.o + tokq * 1024 + h * 128 + d0) = w;
;             }
	v_pk_mul_f32 v[40:41], v[40:41], v[70:71] op_sel_hi:[1,0]
	v_pk_mul_f32 v[40:41], v[40:41], v[216:217]
	v_pk_mul_f32 v[40:41], v[40:41], v[100:101]
	v_pk_mul_f32 v[42:43], v[42:43], v[70:71] op_sel_hi:[1,0]
	v_pk_mul_f32 v[42:43], v[42:43], v[218:219]
	v_pk_mul_f32 v[42:43], v[42:43], v[102:103]
	v_cvt_pk_bf16_f32 v96, v40, v41
	v_cvt_pk_bf16_f32 v97, v42, v43
	global_store_dwordx2 v[78:79], v[96:97], off offset:96
	ds_read_b128 v[216:219], v72 offset:224
	v_lshlrev_b32_e32 v96, 16, v214
	v_and_b32_e32 v97, 0xffff0000, v214
	v_lshlrev_b32_e32 v98, 16, v215
	v_and_b32_e32 v99, 0xffff0000, v215
	v_pk_mul_f32 v[104:105], v[96:97], s[16:17] op_sel_hi:[1,0]
	v_pk_mul_f32 v[106:107], v[98:99], s[16:17] op_sel_hi:[1,0]
	v_exp_f32_e32 v104, v104
	v_exp_f32_e32 v105, v105
	v_exp_f32_e32 v106, v106
	v_exp_f32_e32 v107, v107
	v_pk_add_f32 v[104:105], v[104:105], s[18:19] op_sel_hi:[1,0]
	v_pk_add_f32 v[106:107], v[106:107], s[18:19] op_sel_hi:[1,0]
	v_div_scale_f32 v108, s[0:1], v104, v104, v96
	v_div_scale_f32 v109, s[0:1], v105, v105, v97
	v_div_scale_f32 v110, s[0:1], v106, v106, v98
	v_div_scale_f32 v111, s[0:1], v107, v107, v99
	v_rcp_f32_e32 v112, v108
	v_rcp_f32_e32 v113, v109
	v_rcp_f32_e32 v114, v110
	v_rcp_f32_e32 v115, v111
	v_pk_fma_f32 v[100:101], v[108:109], v[112:113], s[18:19] op_sel_hi:[1,1,0] neg_lo:[1,0,0] neg_hi:[1,0,0]
	v_pk_fma_f32 v[102:103], v[110:111], v[114:115], s[18:19] op_sel_hi:[1,1,0] neg_lo:[1,0,0] neg_hi:[1,0,0]
	v_pk_fma_f32 v[112:113], v[100:101], v[112:113], v[112:113]
	v_pk_fma_f32 v[114:115], v[102:103], v[114:115], v[114:115]
	v_div_scale_f32 v116, s[2:3], v96, v104, v96
	v_div_scale_f32 v117, vcc, v97, v105, v97
	v_pk_mul_f32 v[100:101], v[116:117], v[112:113]
	v_pk_fma_f32 v[120:121], v[108:109], v[100:101], v[116:117] neg_lo:[1,0,0] neg_hi:[1,0,0]
	v_pk_fma_f32 v[100:101], v[120:121], v[112:113], v[100:101]
	v_pk_fma_f32 v[120:121], v[108:109], v[100:101], v[116:117] neg_lo:[1,0,0] neg_hi:[1,0,0]
	v_div_fmas_f32 v121, v121, v113, v101
	v_div_fixup_f32 v101, v121, v105, v97
	s_mov_b64 vcc, s[2:3]
	s_nop 1
	v_div_fmas_f32 v120, v120, v112, v100
	v_div_fixup_f32 v100, v120, v104, v96
	v_div_scale_f32 v118, s[2:3], v98, v106, v98
	v_div_scale_f32 v119, vcc, v99, v107, v99
	v_pk_mul_f32 v[102:103], v[118:119], v[114:115]
	v_pk_fma_f32 v[122:123], v[110:111], v[102:103], v[118:119] neg_lo:[1,0,0] neg_hi:[1,0,0]
	v_pk_fma_f32 v[102:103], v[122:123], v[114:115], v[102:103]
	v_pk_fma_f32 v[122:123], v[110:111], v[102:103], v[118:119] neg_lo:[1,0,0] neg_hi:[1,0,0]
	v_div_fmas_f32 v123, v123, v115, v103
	v_div_fixup_f32 v103, v123, v107, v99
	s_mov_b64 vcc, s[2:3]
	s_nop 1
	v_div_fmas_f32 v122, v122, v114, v102
	v_div_fixup_f32 v102, v122, v106, v98
	s_waitcnt lgkmcnt(0)
	v_pk_mul_f32 v[44:45], v[44:45], v[70:71] op_sel_hi:[1,0]
	v_pk_mul_f32 v[44:45], v[44:45], v[216:217]
	v_pk_mul_f32 v[44:45], v[44:45], v[100:101]
	v_pk_mul_f32 v[46:47], v[46:47], v[70:71] op_sel_hi:[1,0]
	v_pk_mul_f32 v[46:47], v[46:47], v[218:219]
	v_pk_mul_f32 v[46:47], v[46:47], v[102:103]
	v_cvt_pk_bf16_f32 v96, v44, v45
	v_cvt_pk_bf16_f32 v97, v46, v47
	global_store_dwordx2 v[78:79], v[96:97], off offset:112
	s_branch .LBB0_450
.Ldt_c1:
	ds_write2st64_b32 v67, v48, v49 offset0:0 offset1:1
	ds_write2st64_b32 v67, v50, v51 offset0:2 offset1:3
	ds_write2st64_b32 v67, v52, v53 offset0:4 offset1:5
	ds_write2st64_b32 v67, v54, v55 offset0:6 offset1:7
	ds_write2st64_b32 v67, v56, v57 offset0:8 offset1:9
	ds_write2st64_b32 v67, v58, v59 offset0:10 offset1:11
	ds_write2st64_b32 v67, v60, v61 offset0:12 offset1:13
	ds_write2st64_b32 v67, v62, v63 offset0:14 offset1:15
	ds_write2st64_b32 v67, v32, v33 offset0:16 offset1:17
	ds_write2st64_b32 v67, v34, v35 offset0:18 offset1:19
	ds_write2st64_b32 v67, v36, v37 offset0:20 offset1:21
	ds_write2st64_b32 v67, v38, v39 offset0:22 offset1:23
	ds_write2st64_b32 v67, v40, v41 offset0:24 offset1:25
	ds_write2st64_b32 v67, v42, v43 offset0:26 offset1:27
	ds_write2st64_b32 v67, v44, v45 offset0:28 offset1:29
	ds_write2st64_b32 v67, v46, v47 offset0:30 offset1:31
	s_waitcnt lgkmcnt(0)
	s_barrier
	ds_read2st64_b32 v[80:81], v67 offset0:32 offset1:33
	ds_read2st64_b32 v[82:83], v67 offset0:34 offset1:35
	ds_read2st64_b32 v[84:85], v67 offset0:36 offset1:37
	ds_read2st64_b32 v[86:87], v67 offset0:38 offset1:39
	ds_read2st64_b32 v[88:89], v67 offset0:40 offset1:41
	ds_read2st64_b32 v[90:91], v67 offset0:42 offset1:43
	ds_read2st64_b32 v[92:93], v67 offset0:44 offset1:45
	ds_read2st64_b32 v[94:95], v67 offset0:46 offset1:47
	s_waitcnt lgkmcnt(0)
	v_pk_add_f32 v[16:17], v[16:17], v[80:81]
	v_pk_add_f32 v[18:19], v[18:19], v[82:83]
	v_pk_add_f32 v[20:21], v[20:21], v[84:85]
	v_pk_add_f32 v[22:23], v[22:23], v[86:87]
	v_pk_add_f32 v[24:25], v[24:25], v[88:89]
	v_pk_add_f32 v[26:27], v[26:27], v[90:91]
	v_pk_add_f32 v[28:29], v[28:29], v[92:93]
	v_pk_add_f32 v[30:31], v[30:31], v[94:95]
	v_pk_mul_f32 v[76:77], v[16:17], v[16:17]
	v_pk_fma_f32 v[76:77], v[18:19], v[18:19], v[76:77]
	v_pk_fma_f32 v[76:77], v[20:21], v[20:21], v[76:77]
	v_pk_fma_f32 v[76:77], v[22:23], v[22:23], v[76:77]
	v_pk_fma_f32 v[76:77], v[24:25], v[24:25], v[76:77]
	v_pk_fma_f32 v[76:77], v[26:27], v[26:27], v[76:77]
	v_pk_fma_f32 v[76:77], v[28:29], v[28:29], v[76:77]
	v_pk_fma_f32 v[76:77], v[30:31], v[30:31], v[76:77]
	ds_read2st64_b32 v[80:81], v67 offset0:48 offset1:49
	ds_read2st64_b32 v[82:83], v67 offset0:50 offset1:51
	ds_read2st64_b32 v[84:85], v67 offset0:52 offset1:53
	ds_read2st64_b32 v[86:87], v67 offset0:54 offset1:55
	ds_read2st64_b32 v[88:89], v67 offset0:56 offset1:57
	ds_read2st64_b32 v[90:91], v67 offset0:58 offset1:59
	ds_read2st64_b32 v[92:93], v67 offset0:60 offset1:61
	ds_read2st64_b32 v[94:95], v67 offset0:62 offset1:63
	s_waitcnt lgkmcnt(0)
	v_pk_add_f32 v[0:1], v[0:1], v[80:81]
	v_pk_add_f32 v[2:3], v[2:3], v[82:83]
	v_pk_add_f32 v[4:5], v[4:5], v[84:85]
	v_pk_add_f32 v[6:7], v[6:7], v[86:87]
	v_pk_add_f32 v[8:9], v[8:9], v[88:89]
	v_pk_add_f32 v[10:11], v[10:11], v[90:91]
	v_pk_add_f32 v[12:13], v[12:13], v[92:93]
	v_pk_add_f32 v[14:15], v[14:15], v[94:95]
	v_pk_fma_f32 v[76:77], v[0:1], v[0:1], v[76:77]
	v_pk_fma_f32 v[76:77], v[2:3], v[2:3], v[76:77]
	v_pk_fma_f32 v[76:77], v[4:5], v[4:5], v[76:77]
	v_pk_fma_f32 v[76:77], v[6:7], v[6:7], v[76:77]
	v_pk_fma_f32 v[76:77], v[8:9], v[8:9], v[76:77]
	v_pk_fma_f32 v[76:77], v[10:11], v[10:11], v[76:77]
	v_pk_fma_f32 v[76:77], v[12:13], v[12:13], v[76:77]
	v_pk_fma_f32 v[76:77], v[14:15], v[14:15], v[76:77]
	v_add_f32_e32 v69, v76, v77
	ds_bpermute_b32 v72, v244, v69
	s_waitcnt lgkmcnt(0)
	v_add_f32_e32 v69, v69, v72
	ds_write_b32 v68, v69
	s_waitcnt lgkmcnt(0)
	s_barrier
; __device__ __forceinline__ float bflo(unsigned w) { return __uint_as_float(w << 16); }
; __device__ __forceinline__ float bfhi(unsigned w) { return __uint_as_float(w & 0xffff0000u); }
; __device__ __forceinline__ float silu_f(float x) { return x / (1.0f + __expf(-x)); }
; __device__ void da_unit(char* lds, const Params& p, int layer, int unit) {
;     ...
;         ss += __shfl_xor(ss, 32);
;         const float rstd = rsqrtf(ss * (1.0f / 128.0f) + RMS_EPS) * (1.0f - p.lam_init[layer]);
;         const float* sg = (const float*)(lds + LDS_SG_OFF);
;         __builtin_amdgcn_sched_barrier(0);
; #pragma unroll
;         for (int k = 0; k < 4; ++k)
; #pragma unroll
;             for (int g = 0; g < 4; ++g) {
;                 const int d0 = 32 * k + 8 * g + 4 * h2;
;                 const f32x4 gg = *(const f32x4*)(sg + d0);
;                 const u32x2 gw = gwv[k * 4 + g];
;                 const float o0 = O[k][4 * g + 0] * rstd * gg[0] * silu_f(bflo(gw.x));
;                 const float o1 = O[k][4 * g + 1] * rstd * gg[1] * silu_f(bfhi(gw.x));
;                 const float o2 = O[k][4 * g + 2] * rstd * gg[2] * silu_f(bflo(gw.y));
;                 const float o3 = O[k][4 * g + 3] * rstd * gg[3] * silu_f(bfhi(gw.y));
;                 u32x2 w; w.x = cvt_pk_bf16(o0, o1); w.y = cvt_pk_bf16(o2, o3);
;                 *(u32x2*)(p.o + tokq * 1024 + h * 128 + d0) = w;
;             }
	v_add_u32_e32 v73, 0xffffff00, v68
	ds_read_b32 v72, v73
	v_mov_b32_e32 v74, 0x358637bd
	v_sub_f32_e64 v75, 1.0, s2
	s_waitcnt lgkmcnt(0)
	v_add_f32_e32 v69, v69, v72
	v_fmamk_f32 v69, v69, 0x3c000000, v74
	v_rsq_f32_e32 v69, v69
	s_nop 0
	v_mul_f32_e32 v70, v75, v69
	v_lshl_add_u32 v72, v188, 4, 0
	v_add_u32_e32 v72, 0x26b30, v72
	s_waitcnt vmcnt(0)
	s_mov_b32 s16, 0xbfb8aa3b
	s_mov_b32 s18, 1.0
	ds_read_b128 v[216:219], v72 offset:256
	v_lshlrev_b32_e32 v96, 16, v200
	v_and_b32_e32 v97, 0xffff0000, v200
	v_lshlrev_b32_e32 v98, 16, v201
	v_and_b32_e32 v99, 0xffff0000, v201
	v_pk_mul_f32 v[104:105], v[96:97], s[16:17] op_sel_hi:[1,0]
	v_pk_mul_f32 v[106:107], v[98:99], s[16:17] op_sel_hi:[1,0]
	v_exp_f32_e32 v104, v104
	v_exp_f32_e32 v105, v105
	v_exp_f32_e32 v106, v106
	v_exp_f32_e32 v107, v107
	v_pk_add_f32 v[104:105], v[104:105], s[18:19] op_sel_hi:[1,0]
	v_pk_add_f32 v[106:107], v[106:107], s[18:19] op_sel_hi:[1,0]
	v_div_scale_f32 v108, s[0:1], v104, v104, v96
	v_div_scale_f32 v109, s[0:1], v105, v105, v97
	v_div_scale_f32 v110, s[0:1], v106, v106, v98
	v_div_scale_f32 v111, s[0:1], v107, v107, v99
	v_rcp_f32_e32 v112, v108
	v_rcp_f32_e32 v113, v109
	v_rcp_f32_e32 v114, v110
	v_rcp_f32_e32 v115, v111
	v_pk_fma_f32 v[100:101], v[108:109], v[112:113], s[18:19] op_sel_hi:[1,1,0] neg_lo:[1,0,0] neg_hi:[1,0,0]
	v_pk_fma_f32 v[102:103], v[110:111], v[114:115], s[18:19] op_sel_hi:[1,1,0] neg_lo:[1,0,0] neg_hi:[1,0,0]
	v_pk_fma_f32 v[112:113], v[100:101], v[112:113], v[112:113]
	v_pk_fma_f32 v[114:115], v[102:103], v[114:115], v[114:115]
	v_div_scale_f32 v116, s[2:3], v96, v104, v96
	v_div_scale_f32 v117, vcc, v97, v105, v97
	v_pk_mul_f32 v[100:101], v[116:117], v[112:113]
	v_pk_fma_f32 v[120:121], v[108:109], v[100:101], v[116:117] neg_lo:[1,0,0] neg_hi:[1,0,0]
	v_pk_fma_f32 v[100:101], v[120:121], v[112:113], v[100:101]
	v_pk_fma_f32 v[120:121], v[108:109], v[100:101], v[116:117] neg_lo:[1,0,0] neg_hi:[1,0,0]
	v_div_fmas_f32 v121, v121, v113, v101
	v_div_fixup_f32 v101, v121, v105, v97
	s_mov_b64 vcc, s[2:3]
	s_nop 1
	v_div_fmas_f32 v120, v120, v112, v100
	v_div_fixup_f32 v100, v120, v104, v96
	v_div_scale_f32 v118, s[2:3], v98, v106, v98
	v_div_scale_f32 v119, vcc, v99, v107, v99
	v_pk_mul_f32 v[102:103], v[118:119], v[114:115]
	v_pk_fma_f32 v[122:123], v[110:111], v[102:103], v[118:119] neg_lo:[1,0,0] neg_hi:[1,0,0]
	v_pk_fma_f32 v[102:103], v[122:123], v[114:115], v[102:103]
	v_pk_fma_f32 v[122:123], v[110:111], v[102:103], v[118:119] neg_lo:[1,0,0] neg_hi:[1,0,0]
	v_div_fmas_f32 v123, v123, v115, v103
	v_div_fixup_f32 v103, v123, v107, v99
	s_mov_b64 vcc, s[2:3]
	s_nop 1
	v_div_fmas_f32 v122, v122, v114, v102
	v_div_fixup_f32 v102, v122, v106, v98
	s_waitcnt lgkmcnt(0)
	v_pk_mul_f32 v[16:17], v[16:17], v[70:71] op_sel_hi:[1,0]
	v_pk_mul_f32 v[16:17], v[16:17], v[216:217]
	v_pk_mul_f32 v[16:17], v[16:17], v[100:101]
	v_pk_mul_f32 v[18:19], v[18:19], v[70:71] op_sel_hi:[1,0]
	v_pk_mul_f32 v[18:19], v[18:19], v[218:219]
	v_pk_mul_f32 v[18:19], v[18:19], v[102:103]
	v_cvt_pk_bf16_f32 v96, v16, v17
	v_cvt_pk_bf16_f32 v97, v18, v19
	global_store_dwordx2 v[78:79], v[96:97], off offset:0
	ds_read_b128 v[216:219], v72 offset:288
	v_lshlrev_b32_e32 v96, 16, v202
	v_and_b32_e32 v97, 0xffff0000, v202
	v_lshlrev_b32_e32 v98, 16, v203
	v_and_b32_e32 v99, 0xffff0000, v203
	v_pk_mul_f32 v[104:105], v[96:97], s[16:17] op_sel_hi:[1,0]
	v_pk_mul_f32 v[106:107], v[98:99], s[16:17] op_sel_hi:[1,0]
	v_exp_f32_e32 v104, v104
	v_exp_f32_e32 v105, v105
	v_exp_f32_e32 v106, v106
	v_exp_f32_e32 v107, v107
	v_pk_add_f32 v[104:105], v[104:105], s[18:19] op_sel_hi:[1,0]
	v_pk_add_f32 v[106:107], v[106:107], s[18:19] op_sel_hi:[1,0]
	v_div_scale_f32 v108, s[0:1], v104, v104, v96
	v_div_scale_f32 v109, s[0:1], v105, v105, v97
	v_div_scale_f32 v110, s[0:1], v106, v106, v98
	v_div_scale_f32 v111, s[0:1], v107, v107, v99
	v_rcp_f32_e32 v112, v108
	v_rcp_f32_e32 v113, v109
	v_rcp_f32_e32 v114, v110
	v_rcp_f32_e32 v115, v111
	v_pk_fma_f32 v[100:101], v[108:109], v[112:113], s[18:19] op_sel_hi:[1,1,0] neg_lo:[1,0,0] neg_hi:[1,0,0]
	v_pk_fma_f32 v[102:103], v[110:111], v[114:115], s[18:19] op_sel_hi:[1,1,0] neg_lo:[1,0,0] neg_hi:[1,0,0]
	v_pk_fma_f32 v[112:113], v[100:101], v[112:113], v[112:113]
	v_pk_fma_f32 v[114:115], v[102:103], v[114:115], v[114:115]
	v_div_scale_f32 v116, s[2:3], v96, v104, v96
	v_div_scale_f32 v117, vcc, v97, v105, v97
	v_pk_mul_f32 v[100:101], v[116:117], v[112:113]
	v_pk_fma_f32 v[120:121], v[108:109], v[100:101], v[116:117] neg_lo:[1,0,0] neg_hi:[1,0,0]
	v_pk_fma_f32 v[100:101], v[120:121], v[112:113], v[100:101]
	v_pk_fma_f32 v[120:121], v[108:109], v[100:101], v[116:117] neg_lo:[1,0,0] neg_hi:[1,0,0]
	v_div_fmas_f32 v121, v121, v113, v101
	v_div_fixup_f32 v101, v121, v105, v97
	s_mov_b64 vcc, s[2:3]
	s_nop 1
	v_div_fmas_f32 v120, v120, v112, v100
	v_div_fixup_f32 v100, v120, v104, v96
	v_div_scale_f32 v118, s[2:3], v98, v106, v98
	v_div_scale_f32 v119, vcc, v99, v107, v99
	v_pk_mul_f32 v[102:103], v[118:119], v[114:115]
	v_pk_fma_f32 v[122:123], v[110:111], v[102:103], v[118:119] neg_lo:[1,0,0] neg_hi:[1,0,0]
	v_pk_fma_f32 v[102:103], v[122:123], v[114:115], v[102:103]
	v_pk_fma_f32 v[122:123], v[110:111], v[102:103], v[118:119] neg_lo:[1,0,0] neg_hi:[1,0,0]
	v_div_fmas_f32 v123, v123, v115, v103
	v_div_fixup_f32 v103, v123, v107, v99
	s_mov_b64 vcc, s[2:3]
	s_nop 1
	v_div_fmas_f32 v122, v122, v114, v102
	v_div_fixup_f32 v102, v122, v106, v98
	s_waitcnt lgkmcnt(0)
; __device__ __forceinline__ float bflo(unsigned w) { return __uint_as_float(w << 16); }
; __device__ __forceinline__ float bfhi(unsigned w) { return __uint_as_float(w & 0xffff0000u); }
; __device__ __forceinline__ float silu_f(float x) { return x / (1.0f + __expf(-x)); }
; __device__ void da_unit(char* lds, const Params& p, int layer, int unit) {
;     ...
;             for (int g = 0; g < 4; ++g) {
;                 const int d0 = 32 * k + 8 * g + 4 * h2;
;                 const f32x4 gg = *(const f32x4*)(sg + d0);
;                 const u32x2 gw = gwv[k * 4 + g];
;                 const float o0 = O[k][4 * g + 0] * rstd * gg[0] * silu_f(bflo(gw.x));
;                 const float o1 = O[k][4 * g + 1] * rstd * gg[1] * silu_f(bfhi(gw.x));
;                 const float o2 = O[k][4 * g + 2] * rstd * gg[2] * silu_f(bflo(gw.y));
;                 const float o3 = O[k][4 * g + 3] * rstd * gg[3] * silu_f(bfhi(gw.y));
;                 u32x2 w; w.x = cvt_pk_bf16(o0, o1); w.y = cvt_pk_bf16(o2, o3);
;                 *(u32x2*)(p.o + tokq * 1024 + h * 128 + d0) = w;
;             }
	v_pk_mul_f32 v[20:21], v[20:21], v[70:71] op_sel_hi:[1,0]
	v_pk_mul_f32 v[20:21], v[20:21], v[216:217]
	v_pk_mul_f32 v[20:21], v[20:21], v[100:101]
	v_pk_mul_f32 v[22:23], v[22:23], v[70:71] op_sel_hi:[1,0]
	v_pk_mul_f32 v[22:23], v[22:23], v[218:219]
	v_pk_mul_f32 v[22:23], v[22:23], v[102:103]
	v_cvt_pk_bf16_f32 v96, v20, v21
	v_cvt_pk_bf16_f32 v97, v22, v23
	global_store_dwordx2 v[78:79], v[96:97], off offset:16
	ds_read_b128 v[216:219], v72 offset:320
	v_lshlrev_b32_e32 v96, 16, v204
	v_and_b32_e32 v97, 0xffff0000, v204
	v_lshlrev_b32_e32 v98, 16, v205
	v_and_b32_e32 v99, 0xffff0000, v205
	v_pk_mul_f32 v[104:105], v[96:97], s[16:17] op_sel_hi:[1,0]
	v_pk_mul_f32 v[106:107], v[98:99], s[16:17] op_sel_hi:[1,0]
	v_exp_f32_e32 v104, v104
	v_exp_f32_e32 v105, v105
	v_exp_f32_e32 v106, v106
	v_exp_f32_e32 v107, v107
	v_pk_add_f32 v[104:105], v[104:105], s[18:19] op_sel_hi:[1,0]
	v_pk_add_f32 v[106:107], v[106:107], s[18:19] op_sel_hi:[1,0]
	v_div_scale_f32 v108, s[0:1], v104, v104, v96
	v_div_scale_f32 v109, s[0:1], v105, v105, v97
	v_div_scale_f32 v110, s[0:1], v106, v106, v98
	v_div_scale_f32 v111, s[0:1], v107, v107, v99
	v_rcp_f32_e32 v112, v108
	v_rcp_f32_e32 v113, v109
	v_rcp_f32_e32 v114, v110
	v_rcp_f32_e32 v115, v111
	v_pk_fma_f32 v[100:101], v[108:109], v[112:113], s[18:19] op_sel_hi:[1,1,0] neg_lo:[1,0,0] neg_hi:[1,0,0]
	v_pk_fma_f32 v[102:103], v[110:111], v[114:115], s[18:19] op_sel_hi:[1,1,0] neg_lo:[1,0,0] neg_hi:[1,0,0]
	v_pk_fma_f32 v[112:113], v[100:101], v[112:113], v[112:113]
	v_pk_fma_f32 v[114:115], v[102:103], v[114:115], v[114:115]
	v_div_scale_f32 v116, s[2:3], v96, v104, v96
	v_div_scale_f32 v117, vcc, v97, v105, v97
	v_pk_mul_f32 v[100:101], v[116:117], v[112:113]
	v_pk_fma_f32 v[120:121], v[108:109], v[100:101], v[116:117] neg_lo:[1,0,0] neg_hi:[1,0,0]
	v_pk_fma_f32 v[100:101], v[120:121], v[112:113], v[100:101]
	v_pk_fma_f32 v[120:121], v[108:109], v[100:101], v[116:117] neg_lo:[1,0,0] neg_hi:[1,0,0]
	v_div_fmas_f32 v121, v121, v113, v101
	v_div_fixup_f32 v101, v121, v105, v97
	s_mov_b64 vcc, s[2:3]
	s_nop 1
	v_div_fmas_f32 v120, v120, v112, v100
	v_div_fixup_f32 v100, v120, v104, v96
	v_div_scale_f32 v118, s[2:3], v98, v106, v98
	v_div_scale_f32 v119, vcc, v99, v107, v99
	v_pk_mul_f32 v[102:103], v[118:119], v[114:115]
	v_pk_fma_f32 v[122:123], v[110:111], v[102:103], v[118:119] neg_lo:[1,0,0] neg_hi:[1,0,0]
	v_pk_fma_f32 v[102:103], v[122:123], v[114:115], v[102:103]
	v_pk_fma_f32 v[122:123], v[110:111], v[102:103], v[118:119] neg_lo:[1,0,0] neg_hi:[1,0,0]
	v_div_fmas_f32 v123, v123, v115, v103
	v_div_fixup_f32 v103, v123, v107, v99
	s_mov_b64 vcc, s[2:3]
	s_nop 1
	v_div_fmas_f32 v122, v122, v114, v102
	v_div_fixup_f32 v102, v122, v106, v98
	s_waitcnt lgkmcnt(0)
	v_pk_mul_f32 v[24:25], v[24:25], v[70:71] op_sel_hi:[1,0]
	v_pk_mul_f32 v[24:25], v[24:25], v[216:217]
	v_pk_mul_f32 v[24:25], v[24:25], v[100:101]
	v_pk_mul_f32 v[26:27], v[26:27], v[70:71] op_sel_hi:[1,0]
	v_pk_mul_f32 v[26:27], v[26:27], v[218:219]
	v_pk_mul_f32 v[26:27], v[26:27], v[102:103]
	v_cvt_pk_bf16_f32 v96, v24, v25
	v_cvt_pk_bf16_f32 v97, v26, v27
	global_store_dwordx2 v[78:79], v[96:97], off offset:32
	ds_read_b128 v[216:219], v72 offset:352
	v_lshlrev_b32_e32 v96, 16, v206
	v_and_b32_e32 v97, 0xffff0000, v206
	v_lshlrev_b32_e32 v98, 16, v207
	v_and_b32_e32 v99, 0xffff0000, v207
	v_pk_mul_f32 v[104:105], v[96:97], s[16:17] op_sel_hi:[1,0]
	v_pk_mul_f32 v[106:107], v[98:99], s[16:17] op_sel_hi:[1,0]
	v_exp_f32_e32 v104, v104
	v_exp_f32_e32 v105, v105
	v_exp_f32_e32 v106, v106
	v_exp_f32_e32 v107, v107
	v_pk_add_f32 v[104:105], v[104:105], s[18:19] op_sel_hi:[1,0]
	v_pk_add_f32 v[106:107], v[106:107], s[18:19] op_sel_hi:[1,0]
	v_div_scale_f32 v108, s[0:1], v104, v104, v96
	v_div_scale_f32 v109, s[0:1], v105, v105, v97
	v_div_scale_f32 v110, s[0:1], v106, v106, v98
	v_div_scale_f32 v111, s[0:1], v107, v107, v99
	v_rcp_f32_e32 v112, v108
	v_rcp_f32_e32 v113, v109
	v_rcp_f32_e32 v114, v110
	v_rcp_f32_e32 v115, v111
	v_pk_fma_f32 v[100:101], v[108:109], v[112:113], s[18:19] op_sel_hi:[1,1,0] neg_lo:[1,0,0] neg_hi:[1,0,0]
	v_pk_fma_f32 v[102:103], v[110:111], v[114:115], s[18:19] op_sel_hi:[1,1,0] neg_lo:[1,0,0] neg_hi:[1,0,0]
	v_pk_fma_f32 v[112:113], v[100:101], v[112:113], v[112:113]
	v_pk_fma_f32 v[114:115], v[102:103], v[114:115], v[114:115]
	v_div_scale_f32 v116, s[2:3], v96, v104, v96
	v_div_scale_f32 v117, vcc, v97, v105, v97
	v_pk_mul_f32 v[100:101], v[116:117], v[112:113]
	v_pk_fma_f32 v[120:121], v[108:109], v[100:101], v[116:117] neg_lo:[1,0,0] neg_hi:[1,0,0]
	v_pk_fma_f32 v[100:101], v[120:121], v[112:113], v[100:101]
	v_pk_fma_f32 v[120:121], v[108:109], v[100:101], v[116:117] neg_lo:[1,0,0] neg_hi:[1,0,0]
	v_div_fmas_f32 v121, v121, v113, v101
	v_div_fixup_f32 v101, v121, v105, v97
	s_mov_b64 vcc, s[2:3]
	s_nop 1
	v_div_fmas_f32 v120, v120, v112, v100
	v_div_fixup_f32 v100, v120, v104, v96
	v_div_scale_f32 v118, s[2:3], v98, v106, v98
	v_div_scale_f32 v119, vcc, v99, v107, v99
	v_pk_mul_f32 v[102:103], v[118:119], v[114:115]
	v_pk_fma_f32 v[122:123], v[110:111], v[102:103], v[118:119] neg_lo:[1,0,0] neg_hi:[1,0,0]
	v_pk_fma_f32 v[102:103], v[122:123], v[114:115], v[102:103]
	v_pk_fma_f32 v[122:123], v[110:111], v[102:103], v[118:119] neg_lo:[1,0,0] neg_hi:[1,0,0]
	v_div_fmas_f32 v123, v123, v115, v103
	v_div_fixup_f32 v103, v123, v107, v99
	s_mov_b64 vcc, s[2:3]
	s_nop 1
	v_div_fmas_f32 v122, v122, v114, v102
	v_div_fixup_f32 v102, v122, v106, v98
	s_waitcnt lgkmcnt(0)
; __device__ __forceinline__ float bflo(unsigned w) { return __uint_as_float(w << 16); }
; __device__ __forceinline__ float bfhi(unsigned w) { return __uint_as_float(w & 0xffff0000u); }
; __device__ __forceinline__ float silu_f(float x) { return x / (1.0f + __expf(-x)); }
; __device__ void da_unit(char* lds, const Params& p, int layer, int unit) {
;     ...
;             for (int g = 0; g < 4; ++g) {
;                 const int d0 = 32 * k + 8 * g + 4 * h2;
;                 const f32x4 gg = *(const f32x4*)(sg + d0);
;                 const u32x2 gw = gwv[k * 4 + g];
;                 const float o0 = O[k][4 * g + 0] * rstd * gg[0] * silu_f(bflo(gw.x));
;                 const float o1 = O[k][4 * g + 1] * rstd * gg[1] * silu_f(bfhi(gw.x));
;                 const float o2 = O[k][4 * g + 2] * rstd * gg[2] * silu_f(bflo(gw.y));
;                 const float o3 = O[k][4 * g + 3] * rstd * gg[3] * silu_f(bfhi(gw.y));
;                 u32x2 w; w.x = cvt_pk_bf16(o0, o1); w.y = cvt_pk_bf16(o2, o3);
;                 *(u32x2*)(p.o + tokq * 1024 + h * 128 + d0) = w;
;             }
	v_pk_mul_f32 v[28:29], v[28:29], v[70:71] op_sel_hi:[1,0]
	v_pk_mul_f32 v[28:29], v[28:29], v[216:217]
	v_pk_mul_f32 v[28:29], v[28:29], v[100:101]
	v_pk_mul_f32 v[30:31], v[30:31], v[70:71] op_sel_hi:[1,0]
	v_pk_mul_f32 v[30:31], v[30:31], v[218:219]
	v_pk_mul_f32 v[30:31], v[30:31], v[102:103]
	v_cvt_pk_bf16_f32 v96, v28, v29
	v_cvt_pk_bf16_f32 v97, v30, v31
	global_store_dwordx2 v[78:79], v[96:97], off offset:48
	ds_read_b128 v[216:219], v72 offset:384
	v_lshlrev_b32_e32 v96, 16, v208
	v_and_b32_e32 v97, 0xffff0000, v208
	v_lshlrev_b32_e32 v98, 16, v209
	v_and_b32_e32 v99, 0xffff0000, v209
	v_pk_mul_f32 v[104:105], v[96:97], s[16:17] op_sel_hi:[1,0]
	v_pk_mul_f32 v[106:107], v[98:99], s[16:17] op_sel_hi:[1,0]
	v_exp_f32_e32 v104, v104
	v_exp_f32_e32 v105, v105
	v_exp_f32_e32 v106, v106
	v_exp_f32_e32 v107, v107
	v_pk_add_f32 v[104:105], v[104:105], s[18:19] op_sel_hi:[1,0]
	v_pk_add_f32 v[106:107], v[106:107], s[18:19] op_sel_hi:[1,0]
	v_div_scale_f32 v108, s[0:1], v104, v104, v96
	v_div_scale_f32 v109, s[0:1], v105, v105, v97
	v_div_scale_f32 v110, s[0:1], v106, v106, v98
	v_div_scale_f32 v111, s[0:1], v107, v107, v99
	v_rcp_f32_e32 v112, v108
	v_rcp_f32_e32 v113, v109
	v_rcp_f32_e32 v114, v110
	v_rcp_f32_e32 v115, v111
	v_pk_fma_f32 v[100:101], v[108:109], v[112:113], s[18:19] op_sel_hi:[1,1,0] neg_lo:[1,0,0] neg_hi:[1,0,0]
	v_pk_fma_f32 v[102:103], v[110:111], v[114:115], s[18:19] op_sel_hi:[1,1,0] neg_lo:[1,0,0] neg_hi:[1,0,0]
	v_pk_fma_f32 v[112:113], v[100:101], v[112:113], v[112:113]
	v_pk_fma_f32 v[114:115], v[102:103], v[114:115], v[114:115]
	v_div_scale_f32 v116, s[2:3], v96, v104, v96
	v_div_scale_f32 v117, vcc, v97, v105, v97
	v_pk_mul_f32 v[100:101], v[116:117], v[112:113]
	v_pk_fma_f32 v[120:121], v[108:109], v[100:101], v[116:117] neg_lo:[1,0,0] neg_hi:[1,0,0]
	v_pk_fma_f32 v[100:101], v[120:121], v[112:113], v[100:101]
	v_pk_fma_f32 v[120:121], v[108:109], v[100:101], v[116:117] neg_lo:[1,0,0] neg_hi:[1,0,0]
	v_div_fmas_f32 v121, v121, v113, v101
	v_div_fixup_f32 v101, v121, v105, v97
	s_mov_b64 vcc, s[2:3]
	s_nop 1
	v_div_fmas_f32 v120, v120, v112, v100
	v_div_fixup_f32 v100, v120, v104, v96
	v_div_scale_f32 v118, s[2:3], v98, v106, v98
	v_div_scale_f32 v119, vcc, v99, v107, v99
	v_pk_mul_f32 v[102:103], v[118:119], v[114:115]
	v_pk_fma_f32 v[122:123], v[110:111], v[102:103], v[118:119] neg_lo:[1,0,0] neg_hi:[1,0,0]
	v_pk_fma_f32 v[102:103], v[122:123], v[114:115], v[102:103]
	v_pk_fma_f32 v[122:123], v[110:111], v[102:103], v[118:119] neg_lo:[1,0,0] neg_hi:[1,0,0]
	v_div_fmas_f32 v123, v123, v115, v103
	v_div_fixup_f32 v103, v123, v107, v99
	s_mov_b64 vcc, s[2:3]
	s_nop 1
	v_div_fmas_f32 v122, v122, v114, v102
	v_div_fixup_f32 v102, v122, v106, v98
	s_waitcnt lgkmcnt(0)
	v_pk_mul_f32 v[0:1], v[0:1], v[70:71] op_sel_hi:[1,0]
	v_pk_mul_f32 v[0:1], v[0:1], v[216:217]
	v_pk_mul_f32 v[0:1], v[0:1], v[100:101]
	v_pk_mul_f32 v[2:3], v[2:3], v[70:71] op_sel_hi:[1,0]
	v_pk_mul_f32 v[2:3], v[2:3], v[218:219]
	v_pk_mul_f32 v[2:3], v[2:3], v[102:103]
	v_cvt_pk_bf16_f32 v96, v0, v1
	v_cvt_pk_bf16_f32 v97, v2, v3
	global_store_dwordx2 v[78:79], v[96:97], off offset:64
	ds_read_b128 v[216:219], v72 offset:416
	v_lshlrev_b32_e32 v96, 16, v210
	v_and_b32_e32 v97, 0xffff0000, v210
	v_lshlrev_b32_e32 v98, 16, v211
	v_and_b32_e32 v99, 0xffff0000, v211
	v_pk_mul_f32 v[104:105], v[96:97], s[16:17] op_sel_hi:[1,0]
	v_pk_mul_f32 v[106:107], v[98:99], s[16:17] op_sel_hi:[1,0]
	v_exp_f32_e32 v104, v104
	v_exp_f32_e32 v105, v105
	v_exp_f32_e32 v106, v106
	v_exp_f32_e32 v107, v107
	v_pk_add_f32 v[104:105], v[104:105], s[18:19] op_sel_hi:[1,0]
	v_pk_add_f32 v[106:107], v[106:107], s[18:19] op_sel_hi:[1,0]
	v_div_scale_f32 v108, s[0:1], v104, v104, v96
	v_div_scale_f32 v109, s[0:1], v105, v105, v97
	v_div_scale_f32 v110, s[0:1], v106, v106, v98
	v_div_scale_f32 v111, s[0:1], v107, v107, v99
	v_rcp_f32_e32 v112, v108
	v_rcp_f32_e32 v113, v109
	v_rcp_f32_e32 v114, v110
	v_rcp_f32_e32 v115, v111
	v_pk_fma_f32 v[100:101], v[108:109], v[112:113], s[18:19] op_sel_hi:[1,1,0] neg_lo:[1,0,0] neg_hi:[1,0,0]
	v_pk_fma_f32 v[102:103], v[110:111], v[114:115], s[18:19] op_sel_hi:[1,1,0] neg_lo:[1,0,0] neg_hi:[1,0,0]
	v_pk_fma_f32 v[112:113], v[100:101], v[112:113], v[112:113]
	v_pk_fma_f32 v[114:115], v[102:103], v[114:115], v[114:115]
	v_div_scale_f32 v116, s[2:3], v96, v104, v96
	v_div_scale_f32 v117, vcc, v97, v105, v97
	v_pk_mul_f32 v[100:101], v[116:117], v[112:113]
	v_pk_fma_f32 v[120:121], v[108:109], v[100:101], v[116:117] neg_lo:[1,0,0] neg_hi:[1,0,0]
	v_pk_fma_f32 v[100:101], v[120:121], v[112:113], v[100:101]
	v_pk_fma_f32 v[120:121], v[108:109], v[100:101], v[116:117] neg_lo:[1,0,0] neg_hi:[1,0,0]
	v_div_fmas_f32 v121, v121, v113, v101
	v_div_fixup_f32 v101, v121, v105, v97
	s_mov_b64 vcc, s[2:3]
	s_nop 1
	v_div_fmas_f32 v120, v120, v112, v100
	v_div_fixup_f32 v100, v120, v104, v96
	v_div_scale_f32 v118, s[2:3], v98, v106, v98
	v_div_scale_f32 v119, vcc, v99, v107, v99
	v_pk_mul_f32 v[102:103], v[118:119], v[114:115]
	v_pk_fma_f32 v[122:123], v[110:111], v[102:103], v[118:119] neg_lo:[1,0,0] neg_hi:[1,0,0]
	v_pk_fma_f32 v[102:103], v[122:123], v[114:115], v[102:103]
	v_pk_fma_f32 v[122:123], v[110:111], v[102:103], v[118:119] neg_lo:[1,0,0] neg_hi:[1,0,0]
	v_div_fmas_f32 v123, v123, v115, v103
	v_div_fixup_f32 v103, v123, v107, v99
	s_mov_b64 vcc, s[2:3]
	s_nop 1
	v_div_fmas_f32 v122, v122, v114, v102
	v_div_fixup_f32 v102, v122, v106, v98
	s_waitcnt lgkmcnt(0)
; __device__ __forceinline__ float bflo(unsigned w) { return __uint_as_float(w << 16); }
; __device__ __forceinline__ float bfhi(unsigned w) { return __uint_as_float(w & 0xffff0000u); }
; __device__ __forceinline__ float silu_f(float x) { return x / (1.0f + __expf(-x)); }
; __device__ void da_unit(char* lds, const Params& p, int layer, int unit) {
;     ...
;             for (int g = 0; g < 4; ++g) {
;                 const int d0 = 32 * k + 8 * g + 4 * h2;
;                 const f32x4 gg = *(const f32x4*)(sg + d0);
;                 const u32x2 gw = gwv[k * 4 + g];
;                 const float o0 = O[k][4 * g + 0] * rstd * gg[0] * silu_f(bflo(gw.x));
;                 const float o1 = O[k][4 * g + 1] * rstd * gg[1] * silu_f(bfhi(gw.x));
;                 const float o2 = O[k][4 * g + 2] * rstd * gg[2] * silu_f(bflo(gw.y));
;                 const float o3 = O[k][4 * g + 3] * rstd * gg[3] * silu_f(bfhi(gw.y));
;                 u32x2 w; w.x = cvt_pk_bf16(o0, o1); w.y = cvt_pk_bf16(o2, o3);
;                 *(u32x2*)(p.o + tokq * 1024 + h * 128 + d0) = w;
;             }
	v_pk_mul_f32 v[4:5], v[4:5], v[70:71] op_sel_hi:[1,0]
	v_pk_mul_f32 v[4:5], v[4:5], v[216:217]
	v_pk_mul_f32 v[4:5], v[4:5], v[100:101]
	v_pk_mul_f32 v[6:7], v[6:7], v[70:71] op_sel_hi:[1,0]
	v_pk_mul_f32 v[6:7], v[6:7], v[218:219]
	v_pk_mul_f32 v[6:7], v[6:7], v[102:103]
	v_cvt_pk_bf16_f32 v96, v4, v5
	v_cvt_pk_bf16_f32 v97, v6, v7
	global_store_dwordx2 v[78:79], v[96:97], off offset:80
	ds_read_b128 v[216:219], v72 offset:448
	v_lshlrev_b32_e32 v96, 16, v212
	v_and_b32_e32 v97, 0xffff0000, v212
	v_lshlrev_b32_e32 v98, 16, v213
	v_and_b32_e32 v99, 0xffff0000, v213
	v_pk_mul_f32 v[104:105], v[96:97], s[16:17] op_sel_hi:[1,0]
	v_pk_mul_f32 v[106:107], v[98:99], s[16:17] op_sel_hi:[1,0]
	v_exp_f32_e32 v104, v104
	v_exp_f32_e32 v105, v105
	v_exp_f32_e32 v106, v106
	v_exp_f32_e32 v107, v107
	v_pk_add_f32 v[104:105], v[104:105], s[18:19] op_sel_hi:[1,0]
	v_pk_add_f32 v[106:107], v[106:107], s[18:19] op_sel_hi:[1,0]
	v_div_scale_f32 v108, s[0:1], v104, v104, v96
	v_div_scale_f32 v109, s[0:1], v105, v105, v97
	v_div_scale_f32 v110, s[0:1], v106, v106, v98
	v_div_scale_f32 v111, s[0:1], v107, v107, v99
	v_rcp_f32_e32 v112, v108
	v_rcp_f32_e32 v113, v109
	v_rcp_f32_e32 v114, v110
	v_rcp_f32_e32 v115, v111
	v_pk_fma_f32 v[100:101], v[108:109], v[112:113], s[18:19] op_sel_hi:[1,1,0] neg_lo:[1,0,0] neg_hi:[1,0,0]
	v_pk_fma_f32 v[102:103], v[110:111], v[114:115], s[18:19] op_sel_hi:[1,1,0] neg_lo:[1,0,0] neg_hi:[1,0,0]
	v_pk_fma_f32 v[112:113], v[100:101], v[112:113], v[112:113]
	v_pk_fma_f32 v[114:115], v[102:103], v[114:115], v[114:115]
	v_div_scale_f32 v116, s[2:3], v96, v104, v96
	v_div_scale_f32 v117, vcc, v97, v105, v97
	v_pk_mul_f32 v[100:101], v[116:117], v[112:113]
	v_pk_fma_f32 v[120:121], v[108:109], v[100:101], v[116:117] neg_lo:[1,0,0] neg_hi:[1,0,0]
	v_pk_fma_f32 v[100:101], v[120:121], v[112:113], v[100:101]
	v_pk_fma_f32 v[120:121], v[108:109], v[100:101], v[116:117] neg_lo:[1,0,0] neg_hi:[1,0,0]
	v_div_fmas_f32 v121, v121, v113, v101
	v_div_fixup_f32 v101, v121, v105, v97
	s_mov_b64 vcc, s[2:3]
	s_nop 1
	v_div_fmas_f32 v120, v120, v112, v100
	v_div_fixup_f32 v100, v120, v104, v96
	v_div_scale_f32 v118, s[2:3], v98, v106, v98
	v_div_scale_f32 v119, vcc, v99, v107, v99
	v_pk_mul_f32 v[102:103], v[118:119], v[114:115]
	v_pk_fma_f32 v[122:123], v[110:111], v[102:103], v[118:119] neg_lo:[1,0,0] neg_hi:[1,0,0]
	v_pk_fma_f32 v[102:103], v[122:123], v[114:115], v[102:103]
	v_pk_fma_f32 v[122:123], v[110:111], v[102:103], v[118:119] neg_lo:[1,0,0] neg_hi:[1,0,0]
	v_div_fmas_f32 v123, v123, v115, v103
	v_div_fixup_f32 v103, v123, v107, v99
	s_mov_b64 vcc, s[2:3]
	s_nop 1
	v_div_fmas_f32 v122, v122, v114, v102
	v_div_fixup_f32 v102, v122, v106, v98
	s_waitcnt lgkmcnt(0)
	v_pk_mul_f32 v[8:9], v[8:9], v[70:71] op_sel_hi:[1,0]
	v_pk_mul_f32 v[8:9], v[8:9], v[216:217]
	v_pk_mul_f32 v[8:9], v[8:9], v[100:101]
	v_pk_mul_f32 v[10:11], v[10:11], v[70:71] op_sel_hi:[1,0]
	v_pk_mul_f32 v[10:11], v[10:11], v[218:219]
	v_pk_mul_f32 v[10:11], v[10:11], v[102:103]
	v_cvt_pk_bf16_f32 v96, v8, v9
	v_cvt_pk_bf16_f32 v97, v10, v11
	global_store_dwordx2 v[78:79], v[96:97], off offset:96
	ds_read_b128 v[216:219], v72 offset:480
	v_lshlrev_b32_e32 v96, 16, v214
	v_and_b32_e32 v97, 0xffff0000, v214
	v_lshlrev_b32_e32 v98, 16, v215
	v_and_b32_e32 v99, 0xffff0000, v215
	v_pk_mul_f32 v[104:105], v[96:97], s[16:17] op_sel_hi:[1,0]
	v_pk_mul_f32 v[106:107], v[98:99], s[16:17] op_sel_hi:[1,0]
	v_exp_f32_e32 v104, v104
	v_exp_f32_e32 v105, v105
	v_exp_f32_e32 v106, v106
	v_exp_f32_e32 v107, v107
	v_pk_add_f32 v[104:105], v[104:105], s[18:19] op_sel_hi:[1,0]
	v_pk_add_f32 v[106:107], v[106:107], s[18:19] op_sel_hi:[1,0]
	v_div_scale_f32 v108, s[0:1], v104, v104, v96
	v_div_scale_f32 v109, s[0:1], v105, v105, v97
	v_div_scale_f32 v110, s[0:1], v106, v106, v98
	v_div_scale_f32 v111, s[0:1], v107, v107, v99
	v_rcp_f32_e32 v112, v108
	v_rcp_f32_e32 v113, v109
	v_rcp_f32_e32 v114, v110
	v_rcp_f32_e32 v115, v111
	v_pk_fma_f32 v[100:101], v[108:109], v[112:113], s[18:19] op_sel_hi:[1,1,0] neg_lo:[1,0,0] neg_hi:[1,0,0]
	v_pk_fma_f32 v[102:103], v[110:111], v[114:115], s[18:19] op_sel_hi:[1,1,0] neg_lo:[1,0,0] neg_hi:[1,0,0]
	v_pk_fma_f32 v[112:113], v[100:101], v[112:113], v[112:113]
	v_pk_fma_f32 v[114:115], v[102:103], v[114:115], v[114:115]
	v_div_scale_f32 v116, s[2:3], v96, v104, v96
	v_div_scale_f32 v117, vcc, v97, v105, v97
	v_pk_mul_f32 v[100:101], v[116:117], v[112:113]
	v_pk_fma_f32 v[120:121], v[108:109], v[100:101], v[116:117] neg_lo:[1,0,0] neg_hi:[1,0,0]
	v_pk_fma_f32 v[100:101], v[120:121], v[112:113], v[100:101]
	v_pk_fma_f32 v[120:121], v[108:109], v[100:101], v[116:117] neg_lo:[1,0,0] neg_hi:[1,0,0]
	v_div_fmas_f32 v121, v121, v113, v101
	v_div_fixup_f32 v101, v121, v105, v97
	s_mov_b64 vcc, s[2:3]
	s_nop 1
	v_div_fmas_f32 v120, v120, v112, v100
	v_div_fixup_f32 v100, v120, v104, v96
	v_div_scale_f32 v118, s[2:3], v98, v106, v98
	v_div_scale_f32 v119, vcc, v99, v107, v99
	v_pk_mul_f32 v[102:103], v[118:119], v[114:115]
	v_pk_fma_f32 v[122:123], v[110:111], v[102:103], v[118:119] neg_lo:[1,0,0] neg_hi:[1,0,0]
	v_pk_fma_f32 v[102:103], v[122:123], v[114:115], v[102:103]
	v_pk_fma_f32 v[122:123], v[110:111], v[102:103], v[118:119] neg_lo:[1,0,0] neg_hi:[1,0,0]
	v_div_fmas_f32 v123, v123, v115, v103
	v_div_fixup_f32 v103, v123, v107, v99
	s_mov_b64 vcc, s[2:3]
	s_nop 1
	v_div_fmas_f32 v122, v122, v114, v102
	v_div_fixup_f32 v102, v122, v106, v98
	s_waitcnt lgkmcnt(0)
	v_pk_mul_f32 v[12:13], v[12:13], v[70:71] op_sel_hi:[1,0]
	v_pk_mul_f32 v[12:13], v[12:13], v[216:217]
	v_pk_mul_f32 v[12:13], v[12:13], v[100:101]
	v_pk_mul_f32 v[14:15], v[14:15], v[70:71] op_sel_hi:[1,0]
	v_pk_mul_f32 v[14:15], v[14:15], v[218:219]
	v_pk_mul_f32 v[14:15], v[14:15], v[102:103]
	v_cvt_pk_bf16_f32 v96, v12, v13
	v_cvt_pk_bf16_f32 v97, v14, v15
	global_store_dwordx2 v[78:79], v[96:97], off offset:112
	s_branch .LBB0_450
